# added: residual epilogues of out-proj, down-proj and gate GEMMs prefetch their hin loads up front
# speedup vs baseline: 1.0117x; 1.0106x over previous
.LBB0_698:
	v_lshl_add_u32 v142, s2, 8, v144
	v_mov_b32_e32 v141, v195
	v_lshl_or_b32 v140, s0, 8, v146
	v_ashrrev_i32_e32 v143, 31, v142
	v_ashrrev_i32_e32 v141, 31, v140
	v_lshlrev_b64 v[148:149], 10, v[142:143]
	v_lshl_add_u64 v[148:149], v[148:149], 0, v[140:141]
	v_lshlrev_b64 v[152:153], 1, v[148:149]
	v_lshl_add_u64 v[154:155], s[8:9], 0, v[152:153]
	global_load_dwordx4 v[158:161], v[154:155], off
	global_load_dwordx4 v[162:165], v[154:155], off offset:256
	s_mov_b64 s[100:101], 0x8000
	v_lshl_add_u64 v[192:193], v[154:155], 0, s[100:101]
	global_load_dwordx4 v[166:169], v[192:193], off
	global_load_dwordx4 v[170:173], v[192:193], off offset:256
	s_mov_b64 s[100:101], 0x8000
	v_lshl_add_u64 v[192:193], v[192:193], 0, s[100:101]
	global_load_dwordx4 v[174:177], v[192:193], off
	global_load_dwordx4 v[178:181], v[192:193], off offset:256
	s_mov_b64 s[100:101], 0x8000
	v_lshl_add_u64 v[192:193], v[192:193], 0, s[100:101]
	global_load_dwordx4 v[184:187], v[192:193], off
	global_load_dwordx4 v[188:191], v[192:193], off offset:256
	s_mov_b64 s[100:101], 0x28000
	v_lshl_add_u64 v[192:193], v[192:193], 0, s[100:101]
	global_load_dwordx4 v[196:199], v[192:193], off
	global_load_dwordx4 v[210:213], v[192:193], off offset:256
	s_mov_b64 s[100:101], 0x8000
	v_lshl_add_u64 v[192:193], v[192:193], 0, s[100:101]
	global_load_dwordx4 v[214:217], v[192:193], off
	global_load_dwordx4 v[218:221], v[192:193], off offset:256
	s_mov_b64 s[100:101], 0x8000
	v_lshl_add_u64 v[192:193], v[192:193], 0, s[100:101]
	global_load_dwordx4 v[222:225], v[192:193], off
	global_load_dwordx4 v[226:229], v[192:193], off offset:256
	s_mov_b64 s[100:101], 0x8000
	v_lshl_add_u64 v[192:193], v[192:193], 0, s[100:101]
	global_load_dwordx4 v[230:233], v[192:193], off
	global_load_dwordx4 v[234:237], v[192:193], off offset:256
	s_lshl_b32 s36, s0, 2
	s_ashr_i32 s37, s36, 31
	s_waitcnt vmcnt(15)
	v_mov_b32_e32 v148, v158
	v_mov_b32_e32 v149, v159
	v_mov_b32_e32 v150, v160
	v_mov_b32_e32 v151, v161
	v_lshlrev_b32_e32 v156, 16, v148
	v_and_b32_e32 v157, 0xffff0000, v148
	v_lshlrev_b32_e32 v148, 16, v149
	v_and_b32_e32 v149, 0xffff0000, v149
	v_pk_add_f32 v[128:129], v[128:129], v[148:149]
	v_pk_add_f32 v[148:149], v[126:127], v[156:157]
	s_nop 0
	v_cvt_pk_bf16_f32 v126, v148, v149
	v_cvt_pk_bf16_f32 v127, v128, v129
	v_mul_f32_e32 v149, v149, v149
	v_mul_f32_e32 v129, v129, v129
	v_fmac_f32_e32 v149, v148, v148
	v_fmac_f32_e32 v129, v128, v128
	v_add_f32_e32 v156, v149, v129
	v_lshlrev_b32_e32 v128, 16, v150
	v_and_b32_e32 v129, 0xffff0000, v150
	v_lshlrev_b32_e32 v148, 16, v151
	v_and_b32_e32 v149, 0xffff0000, v151
	v_pk_add_f32 v[122:123], v[122:123], v[128:129]
	v_pk_add_f32 v[124:125], v[124:125], v[148:149]
	v_cvt_pk_bf16_f32 v128, v122, v123
	v_mul_f32_e32 v123, v123, v123
	v_fmac_f32_e32 v123, v122, v122
	v_mul_f32_e32 v122, v125, v125
	v_fmac_f32_e32 v122, v124, v124
	v_add_f32_e32 v122, v123, v122
	v_add_f32_e32 v148, v156, v122
	v_lshl_add_u64 v[122:123], s[10:11], 0, v[152:153]
	v_cvt_pk_bf16_f32 v129, v124, v125
	global_store_dwordx4 v[122:123], v[126:129], off
	s_waitcnt vmcnt(15)
	v_mov_b32_e32 v124, v162
	v_mov_b32_e32 v125, v163
	v_mov_b32_e32 v126, v164
	v_mov_b32_e32 v127, v165
	v_lshlrev_b32_e32 v128, 16, v124
	v_and_b32_e32 v129, 0xffff0000, v124
	v_lshlrev_b32_e32 v124, 16, v125
	v_and_b32_e32 v125, 0xffff0000, v125
	v_pk_add_f32 v[120:121], v[120:121], v[124:125]
	v_pk_add_f32 v[124:125], v[118:119], v[128:129]
	s_nop 0
	v_cvt_pk_bf16_f32 v118, v124, v125
	v_cvt_pk_bf16_f32 v119, v120, v121
	v_mul_f32_e32 v125, v125, v125
	v_mul_f32_e32 v121, v121, v121
	v_fmac_f32_e32 v125, v124, v124
	v_fmac_f32_e32 v121, v120, v120
	v_add_f32_e32 v120, v125, v121
	v_add_f32_e32 v128, v148, v120
	v_lshlrev_b32_e32 v120, 16, v126
	v_and_b32_e32 v121, 0xffff0000, v126
	v_lshlrev_b32_e32 v124, 16, v127
	v_and_b32_e32 v125, 0xffff0000, v127
	v_pk_add_f32 v[114:115], v[114:115], v[120:121]
	v_pk_add_f32 v[116:117], v[116:117], v[124:125]
	v_cvt_pk_bf16_f32 v120, v114, v115
	v_mul_f32_e32 v115, v115, v115
	v_fmac_f32_e32 v115, v114, v114
	v_mul_f32_e32 v114, v117, v117
	v_fmac_f32_e32 v114, v116, v116
	v_add_f32_e32 v114, v115, v114
	v_add_f32_e32 v114, v114, v128
	v_mov_b32_e32 v115, v114
	s_nop 1
	v_permlane16_swap_b32_e32 v114, v115
	v_add_f32_e32 v114, v114, v115
	v_mov_b32_e32 v115, v114
	s_nop 1
	v_permlane32_swap_b32_e32 v114, v115
	v_cvt_pk_bf16_f32 v121, v116, v117
	global_store_dwordx4 v[122:123], v[118:121], off offset:256
	s_and_saveexec_b64 s[12:13], s[40:41]
	s_cbranch_execz .LBB0_700
	v_lshlrev_b64 v[116:117], 6, v[142:143]
	v_lshl_add_u64 v[116:117], s[14:15], 0, v[116:117]
	v_lshl_add_u64 v[116:117], s[36:37], 2, v[116:117]
	s_lshl_b32 s0, s55, 2
	v_lshl_add_u64 v[116:117], v[116:117], 0, s[0:1]
	v_add_f32_e32 v114, v114, v115
	global_store_dword v[116:117], v114, off
.LBB0_700:
	s_or_b64 exec, exec, s[12:13]
	v_or_b32_e32 v114, 16, v142
	v_ashrrev_i32_e32 v115, 31, v114
	v_lshlrev_b64 v[116:117], 10, v[114:115]
	v_lshl_add_u64 v[116:117], v[116:117], 0, v[140:141]
	v_lshlrev_b64 v[120:121], 1, v[116:117]
	v_lshl_add_u64 v[122:123], s[8:9], 0, v[120:121]
	s_waitcnt vmcnt(15)
	v_mov_b32_e32 v116, v166
	v_mov_b32_e32 v117, v167
	v_mov_b32_e32 v118, v168
	v_mov_b32_e32 v119, v169
	v_lshlrev_b32_e32 v124, 16, v116
	v_and_b32_e32 v125, 0xffff0000, v116
	v_lshlrev_b32_e32 v116, 16, v117
	v_and_b32_e32 v117, 0xffff0000, v117
	v_pk_add_f32 v[112:113], v[112:113], v[116:117]
	v_pk_add_f32 v[116:117], v[110:111], v[124:125]
	s_nop 0
	v_cvt_pk_bf16_f32 v110, v116, v117
	v_cvt_pk_bf16_f32 v111, v112, v113
	v_mul_f32_e32 v117, v117, v117
	v_mul_f32_e32 v113, v113, v113
	v_fmac_f32_e32 v117, v116, v116
	v_fmac_f32_e32 v113, v112, v112
	v_add_f32_e32 v124, v117, v113
	v_lshlrev_b32_e32 v112, 16, v118
	v_and_b32_e32 v113, 0xffff0000, v118
	v_lshlrev_b32_e32 v116, 16, v119
	v_and_b32_e32 v117, 0xffff0000, v119
	v_pk_add_f32 v[106:107], v[106:107], v[112:113]
	v_pk_add_f32 v[108:109], v[108:109], v[116:117]
	v_cvt_pk_bf16_f32 v112, v106, v107
	v_mul_f32_e32 v107, v107, v107
	v_fmac_f32_e32 v107, v106, v106
	v_mul_f32_e32 v106, v109, v109
	v_fmac_f32_e32 v106, v108, v108
	v_add_f32_e32 v106, v107, v106
	v_add_f32_e32 v116, v124, v106
	v_lshl_add_u64 v[106:107], s[10:11], 0, v[120:121]
	v_cvt_pk_bf16_f32 v113, v108, v109
	global_store_dwordx4 v[106:107], v[110:113], off
	s_waitcnt vmcnt(15)
	v_mov_b32_e32 v108, v170
	v_mov_b32_e32 v109, v171
	v_mov_b32_e32 v110, v172
	v_mov_b32_e32 v111, v173
	v_lshlrev_b32_e32 v112, 16, v108
	v_and_b32_e32 v113, 0xffff0000, v108
	v_lshlrev_b32_e32 v108, 16, v109
	v_and_b32_e32 v109, 0xffff0000, v109
	v_pk_add_f32 v[104:105], v[104:105], v[108:109]
	v_pk_add_f32 v[108:109], v[102:103], v[112:113]
	s_nop 0
	v_cvt_pk_bf16_f32 v102, v108, v109
	v_cvt_pk_bf16_f32 v103, v104, v105
	v_mul_f32_e32 v109, v109, v109
	v_mul_f32_e32 v105, v105, v105
	v_fmac_f32_e32 v109, v108, v108
	v_fmac_f32_e32 v105, v104, v104
	v_add_f32_e32 v104, v109, v105
	v_add_f32_e32 v112, v116, v104
	v_lshlrev_b32_e32 v104, 16, v110
	v_and_b32_e32 v105, 0xffff0000, v110
	v_lshlrev_b32_e32 v108, 16, v111
	v_and_b32_e32 v109, 0xffff0000, v111
	v_pk_add_f32 v[98:99], v[98:99], v[104:105]
	v_pk_add_f32 v[100:101], v[100:101], v[108:109]
	v_cvt_pk_bf16_f32 v104, v98, v99
	v_mul_f32_e32 v99, v99, v99
	v_fmac_f32_e32 v99, v98, v98
	v_mul_f32_e32 v98, v101, v101
	v_fmac_f32_e32 v98, v100, v100
	v_add_f32_e32 v98, v99, v98
	v_add_f32_e32 v98, v98, v112
	v_mov_b32_e32 v99, v98
	s_nop 1
	v_permlane16_swap_b32_e32 v98, v99
	v_add_f32_e32 v98, v98, v99
	v_mov_b32_e32 v99, v98
	s_nop 1
	v_permlane32_swap_b32_e32 v98, v99
	v_cvt_pk_bf16_f32 v105, v100, v101
	global_store_dwordx4 v[106:107], v[102:105], off offset:256
	s_and_saveexec_b64 s[12:13], s[40:41]
	s_cbranch_execz .LBB0_702
	v_lshlrev_b64 v[100:101], 6, v[114:115]
	v_lshl_add_u64 v[100:101], s[14:15], 0, v[100:101]
	v_lshl_add_u64 v[100:101], s[36:37], 2, v[100:101]
	s_lshl_b32 s0, s55, 2
	v_lshl_add_u64 v[100:101], v[100:101], 0, s[0:1]
	v_add_f32_e32 v98, v98, v99
	global_store_dword v[100:101], v98, off
.LBB0_702:
	s_or_b64 exec, exec, s[12:13]
	v_or_b32_e32 v98, 32, v142
	v_ashrrev_i32_e32 v99, 31, v98
	v_lshlrev_b64 v[100:101], 10, v[98:99]
	v_lshl_add_u64 v[100:101], v[100:101], 0, v[140:141]
	v_lshlrev_b64 v[104:105], 1, v[100:101]
	v_lshl_add_u64 v[106:107], s[8:9], 0, v[104:105]
	s_waitcnt vmcnt(15)
	v_mov_b32_e32 v100, v174
	v_mov_b32_e32 v101, v175
	v_mov_b32_e32 v102, v176
	v_mov_b32_e32 v103, v177
	v_lshlrev_b32_e32 v108, 16, v100
	v_and_b32_e32 v109, 0xffff0000, v100
	v_lshlrev_b32_e32 v100, 16, v101
	v_and_b32_e32 v101, 0xffff0000, v101
	v_pk_add_f32 v[96:97], v[96:97], v[100:101]
	v_pk_add_f32 v[100:101], v[94:95], v[108:109]
	s_nop 0
	v_cvt_pk_bf16_f32 v94, v100, v101
	v_cvt_pk_bf16_f32 v95, v96, v97
	v_mul_f32_e32 v101, v101, v101
	v_mul_f32_e32 v97, v97, v97
	v_fmac_f32_e32 v101, v100, v100
	v_fmac_f32_e32 v97, v96, v96
	v_add_f32_e32 v108, v101, v97
	v_lshlrev_b32_e32 v96, 16, v102
	v_and_b32_e32 v97, 0xffff0000, v102
	v_lshlrev_b32_e32 v100, 16, v103
	v_and_b32_e32 v101, 0xffff0000, v103
	v_pk_add_f32 v[90:91], v[90:91], v[96:97]
	v_pk_add_f32 v[92:93], v[92:93], v[100:101]
	v_cvt_pk_bf16_f32 v96, v90, v91
	v_mul_f32_e32 v91, v91, v91
	v_fmac_f32_e32 v91, v90, v90
	v_mul_f32_e32 v90, v93, v93
	v_fmac_f32_e32 v90, v92, v92
	v_add_f32_e32 v90, v91, v90
	v_add_f32_e32 v100, v108, v90
	v_lshl_add_u64 v[90:91], s[10:11], 0, v[104:105]
	v_cvt_pk_bf16_f32 v97, v92, v93
	global_store_dwordx4 v[90:91], v[94:97], off
	s_waitcnt vmcnt(15)
	v_mov_b32_e32 v92, v178
	v_mov_b32_e32 v93, v179
	v_mov_b32_e32 v94, v180
	v_mov_b32_e32 v95, v181
	v_lshlrev_b32_e32 v96, 16, v92
	v_and_b32_e32 v97, 0xffff0000, v92
	v_lshlrev_b32_e32 v92, 16, v93
	v_and_b32_e32 v93, 0xffff0000, v93
	v_pk_add_f32 v[88:89], v[88:89], v[92:93]
	v_pk_add_f32 v[92:93], v[86:87], v[96:97]
	s_nop 0
	v_cvt_pk_bf16_f32 v86, v92, v93
	v_cvt_pk_bf16_f32 v87, v88, v89
	v_mul_f32_e32 v93, v93, v93
	v_mul_f32_e32 v89, v89, v89
	v_fmac_f32_e32 v93, v92, v92
	v_fmac_f32_e32 v89, v88, v88
	v_add_f32_e32 v88, v93, v89
	v_add_f32_e32 v96, v100, v88
	v_lshlrev_b32_e32 v88, 16, v94
	v_and_b32_e32 v89, 0xffff0000, v94
	v_lshlrev_b32_e32 v92, 16, v95
	v_and_b32_e32 v93, 0xffff0000, v95
	v_pk_add_f32 v[82:83], v[82:83], v[88:89]
	v_pk_add_f32 v[84:85], v[84:85], v[92:93]
	v_cvt_pk_bf16_f32 v88, v82, v83
	v_mul_f32_e32 v83, v83, v83
	v_fmac_f32_e32 v83, v82, v82
	v_mul_f32_e32 v82, v85, v85
	v_fmac_f32_e32 v82, v84, v84
	v_add_f32_e32 v82, v83, v82
	v_add_f32_e32 v82, v82, v96
	v_mov_b32_e32 v83, v82
	s_nop 1
	v_permlane16_swap_b32_e32 v82, v83
	v_add_f32_e32 v82, v82, v83
	v_mov_b32_e32 v83, v82
	s_nop 1
	v_permlane32_swap_b32_e32 v82, v83
	v_cvt_pk_bf16_f32 v89, v84, v85
	global_store_dwordx4 v[90:91], v[86:89], off offset:256
	s_and_saveexec_b64 s[12:13], s[40:41]
	s_cbranch_execz .LBB0_704
	v_lshlrev_b64 v[84:85], 6, v[98:99]
	v_lshl_add_u64 v[84:85], s[14:15], 0, v[84:85]
	v_lshl_add_u64 v[84:85], s[36:37], 2, v[84:85]
	s_lshl_b32 s0, s55, 2
	v_lshl_add_u64 v[84:85], v[84:85], 0, s[0:1]
	v_add_f32_e32 v82, v82, v83
	global_store_dword v[84:85], v82, off
.LBB0_704:
	s_or_b64 exec, exec, s[12:13]
	v_or_b32_e32 v82, 48, v142
	v_ashrrev_i32_e32 v83, 31, v82
	v_lshlrev_b64 v[84:85], 10, v[82:83]
	v_lshl_add_u64 v[84:85], v[84:85], 0, v[140:141]
	v_lshlrev_b64 v[88:89], 1, v[84:85]
	v_lshl_add_u64 v[90:91], s[8:9], 0, v[88:89]
	s_waitcnt vmcnt(15)
	v_mov_b32_e32 v84, v184
	v_mov_b32_e32 v85, v185
	v_mov_b32_e32 v86, v186
	v_mov_b32_e32 v87, v187
	v_lshlrev_b32_e32 v92, 16, v84
	v_and_b32_e32 v93, 0xffff0000, v84
	v_lshlrev_b32_e32 v84, 16, v85
	v_and_b32_e32 v85, 0xffff0000, v85
	v_pk_add_f32 v[80:81], v[80:81], v[84:85]
	v_pk_add_f32 v[84:85], v[78:79], v[92:93]
	s_nop 0
	v_cvt_pk_bf16_f32 v78, v84, v85
	v_cvt_pk_bf16_f32 v79, v80, v81
	v_mul_f32_e32 v85, v85, v85
	v_mul_f32_e32 v81, v81, v81
	v_fmac_f32_e32 v85, v84, v84
	v_fmac_f32_e32 v81, v80, v80
	v_add_f32_e32 v92, v85, v81
	v_lshlrev_b32_e32 v80, 16, v86
	v_and_b32_e32 v81, 0xffff0000, v86
	v_lshlrev_b32_e32 v84, 16, v87
	v_and_b32_e32 v85, 0xffff0000, v87
	v_pk_add_f32 v[74:75], v[74:75], v[80:81]
	v_pk_add_f32 v[76:77], v[76:77], v[84:85]
	v_cvt_pk_bf16_f32 v80, v74, v75
	v_mul_f32_e32 v75, v75, v75
	v_fmac_f32_e32 v75, v74, v74
	v_mul_f32_e32 v74, v77, v77
	v_fmac_f32_e32 v74, v76, v76
	v_add_f32_e32 v74, v75, v74
	v_add_f32_e32 v84, v92, v74
	v_lshl_add_u64 v[74:75], s[10:11], 0, v[88:89]
	v_cvt_pk_bf16_f32 v81, v76, v77
	global_store_dwordx4 v[74:75], v[78:81], off
	s_waitcnt vmcnt(15)
	v_mov_b32_e32 v76, v188
	v_mov_b32_e32 v77, v189
	v_mov_b32_e32 v78, v190
	v_mov_b32_e32 v79, v191
	v_lshlrev_b32_e32 v80, 16, v76
	v_and_b32_e32 v81, 0xffff0000, v76
	v_lshlrev_b32_e32 v76, 16, v77
	v_and_b32_e32 v77, 0xffff0000, v77
	v_pk_add_f32 v[72:73], v[72:73], v[76:77]
	v_pk_add_f32 v[76:77], v[70:71], v[80:81]
	s_nop 0
	v_cvt_pk_bf16_f32 v70, v76, v77
	v_cvt_pk_bf16_f32 v71, v72, v73
	v_mul_f32_e32 v77, v77, v77
	v_mul_f32_e32 v73, v73, v73
	v_fmac_f32_e32 v77, v76, v76
	v_fmac_f32_e32 v73, v72, v72
	v_add_f32_e32 v72, v77, v73
	v_add_f32_e32 v80, v84, v72
	v_lshlrev_b32_e32 v72, 16, v78
	v_and_b32_e32 v73, 0xffff0000, v78
	v_lshlrev_b32_e32 v76, 16, v79
	v_and_b32_e32 v77, 0xffff0000, v79
	v_pk_add_f32 v[66:67], v[66:67], v[72:73]
	v_pk_add_f32 v[68:69], v[68:69], v[76:77]
	v_cvt_pk_bf16_f32 v72, v66, v67
	v_mul_f32_e32 v67, v67, v67
	v_fmac_f32_e32 v67, v66, v66
	v_mul_f32_e32 v66, v69, v69
	v_fmac_f32_e32 v66, v68, v68
	v_add_f32_e32 v66, v67, v66
	v_add_f32_e32 v66, v66, v80
	v_mov_b32_e32 v67, v66
	s_nop 1
	v_permlane16_swap_b32_e32 v66, v67
	v_add_f32_e32 v66, v66, v67
	v_mov_b32_e32 v67, v66
	s_nop 1
	v_permlane32_swap_b32_e32 v66, v67
	v_cvt_pk_bf16_f32 v73, v68, v69
	global_store_dwordx4 v[74:75], v[70:73], off offset:256
	s_and_saveexec_b64 s[12:13], s[40:41]
	s_cbranch_execz .LBB0_706
	v_lshlrev_b64 v[68:69], 6, v[82:83]
	v_lshl_add_u64 v[68:69], s[14:15], 0, v[68:69]
	v_lshl_add_u64 v[68:69], s[36:37], 2, v[68:69]
	s_lshl_b32 s0, s55, 2
	v_lshl_add_u64 v[68:69], v[68:69], 0, s[0:1]
	v_add_f32_e32 v66, v66, v67
	global_store_dword v[68:69], v66, off
.LBB0_706:
	s_or_b64 exec, exec, s[12:13]
	v_add_u32_e32 v66, 0x80, v142
	v_ashrrev_i32_e32 v67, 31, v66
	v_lshlrev_b64 v[68:69], 10, v[66:67]
	v_lshl_add_u64 v[68:69], v[68:69], 0, v[140:141]
	v_lshlrev_b64 v[72:73], 1, v[68:69]
	v_lshl_add_u64 v[74:75], s[8:9], 0, v[72:73]
	s_waitcnt vmcnt(15)
	v_mov_b32_e32 v68, v196
	v_mov_b32_e32 v69, v197
	v_mov_b32_e32 v70, v198
	v_mov_b32_e32 v71, v199
	v_lshlrev_b32_e32 v76, 16, v68
	v_and_b32_e32 v77, 0xffff0000, v68
	v_lshlrev_b32_e32 v68, 16, v69
	v_and_b32_e32 v69, 0xffff0000, v69
	v_pk_add_f32 v[64:65], v[64:65], v[68:69]
	v_pk_add_f32 v[68:69], v[62:63], v[76:77]
	s_nop 0
	v_cvt_pk_bf16_f32 v62, v68, v69
	v_cvt_pk_bf16_f32 v63, v64, v65
	v_mul_f32_e32 v69, v69, v69
	v_mul_f32_e32 v65, v65, v65
	v_fmac_f32_e32 v69, v68, v68
	v_fmac_f32_e32 v65, v64, v64
	v_add_f32_e32 v76, v69, v65
	v_lshlrev_b32_e32 v64, 16, v70
	v_and_b32_e32 v65, 0xffff0000, v70
	v_lshlrev_b32_e32 v68, 16, v71
	v_and_b32_e32 v69, 0xffff0000, v71
	v_pk_add_f32 v[58:59], v[58:59], v[64:65]
	v_pk_add_f32 v[60:61], v[60:61], v[68:69]
	v_cvt_pk_bf16_f32 v64, v58, v59
	v_mul_f32_e32 v59, v59, v59
	v_fmac_f32_e32 v59, v58, v58
	v_mul_f32_e32 v58, v61, v61
	v_fmac_f32_e32 v58, v60, v60
	v_add_f32_e32 v58, v59, v58
	v_add_f32_e32 v68, v76, v58
	v_lshl_add_u64 v[58:59], s[10:11], 0, v[72:73]
	v_cvt_pk_bf16_f32 v65, v60, v61
	global_store_dwordx4 v[58:59], v[62:65], off
	s_waitcnt vmcnt(15)
	v_mov_b32_e32 v60, v210
	v_mov_b32_e32 v61, v211
	v_mov_b32_e32 v62, v212
	v_mov_b32_e32 v63, v213
	v_lshlrev_b32_e32 v64, 16, v60
	v_and_b32_e32 v65, 0xffff0000, v60
	v_lshlrev_b32_e32 v60, 16, v61
	v_and_b32_e32 v61, 0xffff0000, v61
	v_pk_add_f32 v[56:57], v[56:57], v[60:61]
	v_pk_add_f32 v[60:61], v[54:55], v[64:65]
	s_nop 0
	v_cvt_pk_bf16_f32 v54, v60, v61
	v_cvt_pk_bf16_f32 v55, v56, v57
	v_mul_f32_e32 v61, v61, v61
	v_mul_f32_e32 v57, v57, v57
	v_fmac_f32_e32 v61, v60, v60
	v_fmac_f32_e32 v57, v56, v56
	v_add_f32_e32 v56, v61, v57
	v_add_f32_e32 v64, v68, v56
	v_lshlrev_b32_e32 v56, 16, v62
	v_and_b32_e32 v57, 0xffff0000, v62
	v_lshlrev_b32_e32 v60, 16, v63
	v_and_b32_e32 v61, 0xffff0000, v63
	v_pk_add_f32 v[50:51], v[50:51], v[56:57]
	v_pk_add_f32 v[52:53], v[52:53], v[60:61]
	v_cvt_pk_bf16_f32 v56, v50, v51
	v_mul_f32_e32 v51, v51, v51
	v_fmac_f32_e32 v51, v50, v50
	v_mul_f32_e32 v50, v53, v53
	v_fmac_f32_e32 v50, v52, v52
	v_add_f32_e32 v50, v51, v50
	v_add_f32_e32 v50, v50, v64
	v_mov_b32_e32 v51, v50
	s_nop 1
	v_permlane16_swap_b32_e32 v50, v51
	v_add_f32_e32 v50, v50, v51
	v_mov_b32_e32 v51, v50
	s_nop 1
	v_permlane32_swap_b32_e32 v50, v51
	v_cvt_pk_bf16_f32 v57, v52, v53
	global_store_dwordx4 v[58:59], v[54:57], off offset:256
	s_and_saveexec_b64 s[12:13], s[40:41]
	s_cbranch_execz .LBB0_708
	v_lshlrev_b64 v[52:53], 6, v[66:67]
	v_lshl_add_u64 v[52:53], s[14:15], 0, v[52:53]
	v_lshl_add_u64 v[52:53], s[36:37], 2, v[52:53]
	s_lshl_b32 s0, s55, 2
	v_lshl_add_u64 v[52:53], v[52:53], 0, s[0:1]
	v_add_f32_e32 v50, v50, v51
	global_store_dword v[52:53], v50, off
.LBB0_708:
	s_or_b64 exec, exec, s[12:13]
	v_add_u32_e32 v50, 0x90, v142
	v_ashrrev_i32_e32 v51, 31, v50
	v_lshlrev_b64 v[52:53], 10, v[50:51]
	v_lshl_add_u64 v[52:53], v[52:53], 0, v[140:141]
	v_lshlrev_b64 v[56:57], 1, v[52:53]
	v_lshl_add_u64 v[58:59], s[8:9], 0, v[56:57]
	s_waitcnt vmcnt(15)
	v_mov_b32_e32 v52, v214
	v_mov_b32_e32 v53, v215
	v_mov_b32_e32 v54, v216
	v_mov_b32_e32 v55, v217
	v_lshlrev_b32_e32 v60, 16, v52
	v_and_b32_e32 v61, 0xffff0000, v52
	v_lshlrev_b32_e32 v52, 16, v53
	v_and_b32_e32 v53, 0xffff0000, v53
	v_pk_add_f32 v[48:49], v[48:49], v[52:53]
	v_pk_add_f32 v[52:53], v[46:47], v[60:61]
	s_nop 0
	v_cvt_pk_bf16_f32 v46, v52, v53
	v_cvt_pk_bf16_f32 v47, v48, v49
	v_mul_f32_e32 v53, v53, v53
	v_mul_f32_e32 v49, v49, v49
	v_fmac_f32_e32 v53, v52, v52
	v_fmac_f32_e32 v49, v48, v48
	v_add_f32_e32 v60, v53, v49
	v_lshlrev_b32_e32 v48, 16, v54
	v_and_b32_e32 v49, 0xffff0000, v54
	v_lshlrev_b32_e32 v52, 16, v55
	v_and_b32_e32 v53, 0xffff0000, v55
	v_pk_add_f32 v[42:43], v[42:43], v[48:49]
	v_pk_add_f32 v[44:45], v[44:45], v[52:53]
	v_cvt_pk_bf16_f32 v48, v42, v43
	v_mul_f32_e32 v43, v43, v43
	v_fmac_f32_e32 v43, v42, v42
	v_mul_f32_e32 v42, v45, v45
	v_fmac_f32_e32 v42, v44, v44
	v_add_f32_e32 v42, v43, v42
	v_add_f32_e32 v52, v60, v42
	v_lshl_add_u64 v[42:43], s[10:11], 0, v[56:57]
	v_cvt_pk_bf16_f32 v49, v44, v45
	global_store_dwordx4 v[42:43], v[46:49], off
	s_waitcnt vmcnt(15)
	v_mov_b32_e32 v44, v218
	v_mov_b32_e32 v45, v219
	v_mov_b32_e32 v46, v220
	v_mov_b32_e32 v47, v221
	v_lshlrev_b32_e32 v48, 16, v44
	v_and_b32_e32 v49, 0xffff0000, v44
	v_lshlrev_b32_e32 v44, 16, v45
	v_and_b32_e32 v45, 0xffff0000, v45
	v_pk_add_f32 v[40:41], v[40:41], v[44:45]
	v_pk_add_f32 v[44:45], v[38:39], v[48:49]
	s_nop 0
	v_cvt_pk_bf16_f32 v38, v44, v45
	v_cvt_pk_bf16_f32 v39, v40, v41
	v_mul_f32_e32 v45, v45, v45
	v_mul_f32_e32 v41, v41, v41
	v_fmac_f32_e32 v45, v44, v44
	v_fmac_f32_e32 v41, v40, v40
	v_add_f32_e32 v40, v45, v41
	v_add_f32_e32 v48, v52, v40
	v_lshlrev_b32_e32 v40, 16, v46
	v_and_b32_e32 v41, 0xffff0000, v46
	v_lshlrev_b32_e32 v44, 16, v47
	v_and_b32_e32 v45, 0xffff0000, v47
	v_pk_add_f32 v[34:35], v[34:35], v[40:41]
	v_pk_add_f32 v[36:37], v[36:37], v[44:45]
	v_cvt_pk_bf16_f32 v40, v34, v35
	v_mul_f32_e32 v35, v35, v35
	v_fmac_f32_e32 v35, v34, v34
	v_mul_f32_e32 v34, v37, v37
	v_fmac_f32_e32 v34, v36, v36
	v_add_f32_e32 v34, v35, v34
	v_add_f32_e32 v34, v34, v48
	v_mov_b32_e32 v35, v34
	s_nop 1
	v_permlane16_swap_b32_e32 v34, v35
	v_add_f32_e32 v34, v34, v35
	v_mov_b32_e32 v35, v34
	s_nop 1
	v_permlane32_swap_b32_e32 v34, v35
	v_cvt_pk_bf16_f32 v41, v36, v37
	global_store_dwordx4 v[42:43], v[38:41], off offset:256
	s_and_saveexec_b64 s[12:13], s[40:41]
	s_cbranch_execz .LBB0_710
	v_lshlrev_b64 v[36:37], 6, v[50:51]
	v_lshl_add_u64 v[36:37], s[14:15], 0, v[36:37]
	v_lshl_add_u64 v[36:37], s[36:37], 2, v[36:37]
	s_lshl_b32 s0, s55, 2
	v_lshl_add_u64 v[36:37], v[36:37], 0, s[0:1]
	v_add_f32_e32 v34, v34, v35
	global_store_dword v[36:37], v34, off
.LBB0_710:
	s_or_b64 exec, exec, s[12:13]
	v_add_u32_e32 v34, 0xa0, v142
	v_ashrrev_i32_e32 v35, 31, v34
	v_lshlrev_b64 v[36:37], 10, v[34:35]
	v_lshl_add_u64 v[36:37], v[36:37], 0, v[140:141]
	v_lshlrev_b64 v[40:41], 1, v[36:37]
	v_lshl_add_u64 v[42:43], s[8:9], 0, v[40:41]
	s_waitcnt vmcnt(15)
	v_mov_b32_e32 v36, v222
	v_mov_b32_e32 v37, v223
	v_mov_b32_e32 v38, v224
	v_mov_b32_e32 v39, v225
	v_lshlrev_b32_e32 v44, 16, v36
	v_and_b32_e32 v45, 0xffff0000, v36
	v_lshlrev_b32_e32 v36, 16, v37
	v_and_b32_e32 v37, 0xffff0000, v37
	v_pk_add_f32 v[32:33], v[32:33], v[36:37]
	v_pk_add_f32 v[36:37], v[30:31], v[44:45]
	s_nop 0
	v_cvt_pk_bf16_f32 v30, v36, v37
	v_cvt_pk_bf16_f32 v31, v32, v33
	v_mul_f32_e32 v37, v37, v37
	v_mul_f32_e32 v33, v33, v33
	v_fmac_f32_e32 v37, v36, v36
	v_fmac_f32_e32 v33, v32, v32
	v_add_f32_e32 v44, v37, v33
	v_lshlrev_b32_e32 v32, 16, v38
	v_and_b32_e32 v33, 0xffff0000, v38
	v_lshlrev_b32_e32 v36, 16, v39
	v_and_b32_e32 v37, 0xffff0000, v39
	v_pk_add_f32 v[26:27], v[26:27], v[32:33]
	v_pk_add_f32 v[28:29], v[28:29], v[36:37]
	v_cvt_pk_bf16_f32 v32, v26, v27
	v_mul_f32_e32 v27, v27, v27
	v_fmac_f32_e32 v27, v26, v26
	v_mul_f32_e32 v26, v29, v29
	v_fmac_f32_e32 v26, v28, v28
	v_add_f32_e32 v26, v27, v26
	v_add_f32_e32 v36, v44, v26
	v_lshl_add_u64 v[26:27], s[10:11], 0, v[40:41]
	v_cvt_pk_bf16_f32 v33, v28, v29
	global_store_dwordx4 v[26:27], v[30:33], off
	s_waitcnt vmcnt(15)
	v_mov_b32_e32 v28, v226
	v_mov_b32_e32 v29, v227
	v_mov_b32_e32 v30, v228
	v_mov_b32_e32 v31, v229
	v_lshlrev_b32_e32 v32, 16, v28
	v_and_b32_e32 v33, 0xffff0000, v28
	v_lshlrev_b32_e32 v28, 16, v29
	v_and_b32_e32 v29, 0xffff0000, v29
	v_pk_add_f32 v[24:25], v[24:25], v[28:29]
	v_pk_add_f32 v[28:29], v[22:23], v[32:33]
	s_nop 0
	v_cvt_pk_bf16_f32 v22, v28, v29
	v_cvt_pk_bf16_f32 v23, v24, v25
	v_mul_f32_e32 v29, v29, v29
	v_mul_f32_e32 v25, v25, v25
	v_fmac_f32_e32 v29, v28, v28
	v_fmac_f32_e32 v25, v24, v24
	v_add_f32_e32 v24, v29, v25
	v_add_f32_e32 v32, v36, v24
	v_lshlrev_b32_e32 v24, 16, v30
	v_and_b32_e32 v25, 0xffff0000, v30
	v_lshlrev_b32_e32 v28, 16, v31
	v_and_b32_e32 v29, 0xffff0000, v31
	v_pk_add_f32 v[18:19], v[18:19], v[24:25]
	v_pk_add_f32 v[20:21], v[20:21], v[28:29]
	v_cvt_pk_bf16_f32 v24, v18, v19
	v_mul_f32_e32 v19, v19, v19
	v_fmac_f32_e32 v19, v18, v18
	v_mul_f32_e32 v18, v21, v21
	v_fmac_f32_e32 v18, v20, v20
	v_add_f32_e32 v18, v19, v18
	v_add_f32_e32 v18, v18, v32
	v_mov_b32_e32 v19, v18
	s_nop 1
	v_permlane16_swap_b32_e32 v18, v19
	v_add_f32_e32 v18, v18, v19
	v_mov_b32_e32 v19, v18
	s_nop 1
	v_permlane32_swap_b32_e32 v18, v19
	v_cvt_pk_bf16_f32 v25, v20, v21
	global_store_dwordx4 v[26:27], v[22:25], off offset:256
	s_and_saveexec_b64 s[12:13], s[40:41]
	s_cbranch_execz .LBB0_712
	v_lshlrev_b64 v[20:21], 6, v[34:35]
	v_lshl_add_u64 v[20:21], s[14:15], 0, v[20:21]
	v_lshl_add_u64 v[20:21], s[36:37], 2, v[20:21]
	s_lshl_b32 s0, s55, 2
	v_lshl_add_u64 v[20:21], v[20:21], 0, s[0:1]
	v_add_f32_e32 v18, v18, v19
	global_store_dword v[20:21], v18, off
.LBB0_712:
	s_or_b64 exec, exec, s[12:13]
	v_add_u32_e32 v18, 0xb0, v142
	v_ashrrev_i32_e32 v19, 31, v18
	v_lshlrev_b64 v[20:21], 10, v[18:19]
	v_lshl_add_u64 v[20:21], v[20:21], 0, v[140:141]
	v_lshlrev_b64 v[24:25], 1, v[20:21]
	v_lshl_add_u64 v[26:27], s[8:9], 0, v[24:25]
	s_waitcnt vmcnt(15)
	v_mov_b32_e32 v20, v230
	v_mov_b32_e32 v21, v231
	v_mov_b32_e32 v22, v232
	v_mov_b32_e32 v23, v233
	v_lshlrev_b32_e32 v28, 16, v20
	v_and_b32_e32 v29, 0xffff0000, v20
	v_lshlrev_b32_e32 v20, 16, v21
	v_and_b32_e32 v21, 0xffff0000, v21
	v_pk_add_f32 v[16:17], v[16:17], v[20:21]
	v_pk_add_f32 v[20:21], v[14:15], v[28:29]
	s_nop 0
	v_cvt_pk_bf16_f32 v14, v20, v21
	v_cvt_pk_bf16_f32 v15, v16, v17
	v_mul_f32_e32 v21, v21, v21
	v_mul_f32_e32 v17, v17, v17
	v_fmac_f32_e32 v21, v20, v20
	v_fmac_f32_e32 v17, v16, v16
	v_add_f32_e32 v28, v21, v17
	v_lshlrev_b32_e32 v16, 16, v22
	v_and_b32_e32 v17, 0xffff0000, v22
	v_lshlrev_b32_e32 v20, 16, v23
	v_and_b32_e32 v21, 0xffff0000, v23
	v_pk_add_f32 v[10:11], v[10:11], v[16:17]
	v_pk_add_f32 v[12:13], v[12:13], v[20:21]
	v_cvt_pk_bf16_f32 v16, v10, v11
	v_mul_f32_e32 v11, v11, v11
	v_fmac_f32_e32 v11, v10, v10
	v_mul_f32_e32 v10, v13, v13
	v_fmac_f32_e32 v10, v12, v12
	v_add_f32_e32 v10, v11, v10
	v_add_f32_e32 v20, v28, v10
	v_lshl_add_u64 v[10:11], s[10:11], 0, v[24:25]
	v_cvt_pk_bf16_f32 v17, v12, v13
	global_store_dwordx4 v[10:11], v[14:17], off
	s_waitcnt vmcnt(15)
	v_mov_b32_e32 v12, v234
	v_mov_b32_e32 v13, v235
	v_mov_b32_e32 v14, v236
	v_mov_b32_e32 v15, v237
	v_lshlrev_b32_e32 v16, 16, v12
	v_and_b32_e32 v17, 0xffff0000, v12
	v_lshlrev_b32_e32 v12, 16, v13
	v_and_b32_e32 v13, 0xffff0000, v13
	v_pk_add_f32 v[8:9], v[8:9], v[12:13]
	v_pk_add_f32 v[12:13], v[6:7], v[16:17]
	s_nop 0
	v_cvt_pk_bf16_f32 v6, v12, v13
	v_cvt_pk_bf16_f32 v7, v8, v9
	v_mul_f32_e32 v13, v13, v13
	v_mul_f32_e32 v9, v9, v9
	v_fmac_f32_e32 v13, v12, v12
	v_fmac_f32_e32 v9, v8, v8
	v_add_f32_e32 v8, v13, v9
	v_add_f32_e32 v16, v20, v8
	v_lshlrev_b32_e32 v8, 16, v14
	v_and_b32_e32 v9, 0xffff0000, v14
	v_lshlrev_b32_e32 v12, 16, v15
	v_and_b32_e32 v13, 0xffff0000, v15
	v_pk_add_f32 v[2:3], v[2:3], v[8:9]
	v_pk_add_f32 v[4:5], v[4:5], v[12:13]
	v_cvt_pk_bf16_f32 v8, v2, v3
	v_mul_f32_e32 v3, v3, v3
	v_fmac_f32_e32 v3, v2, v2
	v_mul_f32_e32 v2, v5, v5
	v_fmac_f32_e32 v2, v4, v4
	v_add_f32_e32 v2, v3, v2
	v_add_f32_e32 v2, v2, v16
	v_mov_b32_e32 v3, v2
	s_nop 1
	v_permlane16_swap_b32_e32 v2, v3
	v_add_f32_e32 v2, v2, v3
	v_mov_b32_e32 v3, v2
	s_nop 1
	v_permlane32_swap_b32_e32 v2, v3
	v_cvt_pk_bf16_f32 v9, v4, v5
	global_store_dwordx4 v[10:11], v[6:9], off offset:256
	s_and_saveexec_b64 s[12:13], s[40:41]
	s_cbranch_execz .LBB0_714
	v_lshlrev_b64 v[4:5], 6, v[18:19]
	v_lshl_add_u64 v[4:5], s[14:15], 0, v[4:5]
	v_lshl_add_u64 v[4:5], s[36:37], 2, v[4:5]
	s_lshl_b32 s0, s55, 2
	v_lshl_add_u64 v[4:5], v[4:5], 0, s[0:1]
	v_add_f32_e32 v2, v2, v3
	global_store_dword v[4:5], v2, off

.LBB0_867:
	v_lshl_add_u32 v142, s2, 8, v144
	v_mov_b32_e32 v141, v195
	v_lshl_or_b32 v140, s0, 8, v146
	v_ashrrev_i32_e32 v143, 31, v142
	v_ashrrev_i32_e32 v141, 31, v140
	v_lshlrev_b64 v[148:149], 10, v[142:143]
	v_lshl_add_u64 v[148:149], v[148:149], 0, v[140:141]
	v_lshlrev_b64 v[152:153], 1, v[148:149]
	v_lshl_add_u64 v[154:155], s[6:7], 0, v[152:153]
	global_load_dwordx4 v[158:161], v[154:155], off
	global_load_dwordx4 v[162:165], v[154:155], off offset:256
	s_mov_b64 s[100:101], 0x8000
	v_lshl_add_u64 v[192:193], v[154:155], 0, s[100:101]
	global_load_dwordx4 v[166:169], v[192:193], off
	global_load_dwordx4 v[170:173], v[192:193], off offset:256
	s_mov_b64 s[100:101], 0x8000
	v_lshl_add_u64 v[192:193], v[192:193], 0, s[100:101]
	global_load_dwordx4 v[174:177], v[192:193], off
	global_load_dwordx4 v[178:181], v[192:193], off offset:256
	s_mov_b64 s[100:101], 0x8000
	v_lshl_add_u64 v[192:193], v[192:193], 0, s[100:101]
	global_load_dwordx4 v[184:187], v[192:193], off
	global_load_dwordx4 v[188:191], v[192:193], off offset:256
	s_mov_b64 s[100:101], 0x28000
	v_lshl_add_u64 v[192:193], v[192:193], 0, s[100:101]
	global_load_dwordx4 v[196:199], v[192:193], off
	global_load_dwordx4 v[210:213], v[192:193], off offset:256
	s_mov_b64 s[100:101], 0x8000
	v_lshl_add_u64 v[192:193], v[192:193], 0, s[100:101]
	global_load_dwordx4 v[214:217], v[192:193], off
	global_load_dwordx4 v[218:221], v[192:193], off offset:256
	s_mov_b64 s[100:101], 0x8000
	v_lshl_add_u64 v[192:193], v[192:193], 0, s[100:101]
	global_load_dwordx4 v[222:225], v[192:193], off
	global_load_dwordx4 v[226:229], v[192:193], off offset:256
	s_mov_b64 s[100:101], 0x8000
	v_lshl_add_u64 v[192:193], v[192:193], 0, s[100:101]
	global_load_dwordx4 v[230:233], v[192:193], off
	global_load_dwordx4 v[234:237], v[192:193], off offset:256
	s_lshl_b32 s36, s0, 2
	s_ashr_i32 s37, s36, 31
	s_waitcnt vmcnt(15)
	v_mov_b32_e32 v148, v158
	v_mov_b32_e32 v149, v159
	v_mov_b32_e32 v150, v160
	v_mov_b32_e32 v151, v161
	v_lshlrev_b32_e32 v156, 16, v148
	v_and_b32_e32 v157, 0xffff0000, v148
	v_lshlrev_b32_e32 v148, 16, v149
	v_and_b32_e32 v149, 0xffff0000, v149
	v_pk_add_f32 v[128:129], v[128:129], v[148:149]
	v_pk_add_f32 v[148:149], v[126:127], v[156:157]
	s_nop 0
	v_cvt_pk_bf16_f32 v126, v148, v149
	v_cvt_pk_bf16_f32 v127, v128, v129
	v_mul_f32_e32 v149, v149, v149
	v_mul_f32_e32 v129, v129, v129
	v_fmac_f32_e32 v149, v148, v148
	v_fmac_f32_e32 v129, v128, v128
	v_add_f32_e32 v156, v149, v129
	v_lshlrev_b32_e32 v128, 16, v150
	v_and_b32_e32 v129, 0xffff0000, v150
	v_lshlrev_b32_e32 v148, 16, v151
	v_and_b32_e32 v149, 0xffff0000, v151
	v_pk_add_f32 v[122:123], v[122:123], v[128:129]
	v_pk_add_f32 v[124:125], v[124:125], v[148:149]
	v_cvt_pk_bf16_f32 v128, v122, v123
	v_mul_f32_e32 v123, v123, v123
	v_fmac_f32_e32 v123, v122, v122
	v_mul_f32_e32 v122, v125, v125
	v_fmac_f32_e32 v122, v124, v124
	v_add_f32_e32 v122, v123, v122
	v_add_f32_e32 v148, v156, v122
	v_lshl_add_u64 v[122:123], s[10:11], 0, v[152:153]
	v_cvt_pk_bf16_f32 v129, v124, v125
	global_store_dwordx4 v[122:123], v[126:129], off
	s_waitcnt vmcnt(15)
	v_mov_b32_e32 v124, v162
	v_mov_b32_e32 v125, v163
	v_mov_b32_e32 v126, v164
	v_mov_b32_e32 v127, v165
	v_lshlrev_b32_e32 v128, 16, v124
	v_and_b32_e32 v129, 0xffff0000, v124
	v_lshlrev_b32_e32 v124, 16, v125
	v_and_b32_e32 v125, 0xffff0000, v125
	v_pk_add_f32 v[120:121], v[120:121], v[124:125]
	v_pk_add_f32 v[124:125], v[118:119], v[128:129]
	s_nop 0
	v_cvt_pk_bf16_f32 v118, v124, v125
	v_cvt_pk_bf16_f32 v119, v120, v121
	v_mul_f32_e32 v125, v125, v125
	v_mul_f32_e32 v121, v121, v121
	v_fmac_f32_e32 v125, v124, v124
	v_fmac_f32_e32 v121, v120, v120
	v_add_f32_e32 v120, v125, v121
	v_add_f32_e32 v128, v148, v120
	v_lshlrev_b32_e32 v120, 16, v126
	v_and_b32_e32 v121, 0xffff0000, v126
	v_lshlrev_b32_e32 v124, 16, v127
	v_and_b32_e32 v125, 0xffff0000, v127
	v_pk_add_f32 v[114:115], v[114:115], v[120:121]
	v_pk_add_f32 v[116:117], v[116:117], v[124:125]
	v_cvt_pk_bf16_f32 v120, v114, v115
	v_mul_f32_e32 v115, v115, v115
	v_fmac_f32_e32 v115, v114, v114
	v_mul_f32_e32 v114, v117, v117
	v_fmac_f32_e32 v114, v116, v116
	v_add_f32_e32 v114, v115, v114
	v_add_f32_e32 v114, v114, v128
	v_mov_b32_e32 v115, v114
	s_nop 1
	v_permlane16_swap_b32_e32 v114, v115
	v_add_f32_e32 v114, v114, v115
	v_mov_b32_e32 v115, v114
	s_nop 1
	v_permlane32_swap_b32_e32 v114, v115
	v_cvt_pk_bf16_f32 v121, v116, v117
	global_store_dwordx4 v[122:123], v[118:121], off offset:256
	s_and_saveexec_b64 s[12:13], s[40:41]
	s_cbranch_execz .LBB0_869
	v_lshlrev_b64 v[116:117], 6, v[142:143]
	v_lshl_add_u64 v[116:117], s[14:15], 0, v[116:117]
	v_lshl_add_u64 v[116:117], s[36:37], 2, v[116:117]
	s_lshl_b32 s0, s55, 2
	v_lshl_add_u64 v[116:117], v[116:117], 0, s[0:1]
	v_add_f32_e32 v114, v114, v115
	global_store_dword v[116:117], v114, off
.LBB0_869:
	s_or_b64 exec, exec, s[12:13]
	v_or_b32_e32 v114, 16, v142
	v_ashrrev_i32_e32 v115, 31, v114
	v_lshlrev_b64 v[116:117], 10, v[114:115]
	v_lshl_add_u64 v[116:117], v[116:117], 0, v[140:141]
	v_lshlrev_b64 v[120:121], 1, v[116:117]
	v_lshl_add_u64 v[122:123], s[6:7], 0, v[120:121]
	s_waitcnt vmcnt(15)
	v_mov_b32_e32 v116, v166
	v_mov_b32_e32 v117, v167
	v_mov_b32_e32 v118, v168
	v_mov_b32_e32 v119, v169
	v_lshlrev_b32_e32 v124, 16, v116
	v_and_b32_e32 v125, 0xffff0000, v116
	v_lshlrev_b32_e32 v116, 16, v117
	v_and_b32_e32 v117, 0xffff0000, v117
	v_pk_add_f32 v[112:113], v[112:113], v[116:117]
	v_pk_add_f32 v[116:117], v[110:111], v[124:125]
	s_nop 0
	v_cvt_pk_bf16_f32 v110, v116, v117
	v_cvt_pk_bf16_f32 v111, v112, v113
	v_mul_f32_e32 v117, v117, v117
	v_mul_f32_e32 v113, v113, v113
	v_fmac_f32_e32 v117, v116, v116
	v_fmac_f32_e32 v113, v112, v112
	v_add_f32_e32 v124, v117, v113
	v_lshlrev_b32_e32 v112, 16, v118
	v_and_b32_e32 v113, 0xffff0000, v118
	v_lshlrev_b32_e32 v116, 16, v119
	v_and_b32_e32 v117, 0xffff0000, v119
	v_pk_add_f32 v[106:107], v[106:107], v[112:113]
	v_pk_add_f32 v[108:109], v[108:109], v[116:117]
	v_cvt_pk_bf16_f32 v112, v106, v107
	v_mul_f32_e32 v107, v107, v107
	v_fmac_f32_e32 v107, v106, v106
	v_mul_f32_e32 v106, v109, v109
	v_fmac_f32_e32 v106, v108, v108
	v_add_f32_e32 v106, v107, v106
	v_add_f32_e32 v116, v124, v106
	v_lshl_add_u64 v[106:107], s[10:11], 0, v[120:121]
	v_cvt_pk_bf16_f32 v113, v108, v109
	global_store_dwordx4 v[106:107], v[110:113], off
	s_waitcnt vmcnt(15)
	v_mov_b32_e32 v108, v170
	v_mov_b32_e32 v109, v171
	v_mov_b32_e32 v110, v172
	v_mov_b32_e32 v111, v173
	v_lshlrev_b32_e32 v112, 16, v108
	v_and_b32_e32 v113, 0xffff0000, v108
	v_lshlrev_b32_e32 v108, 16, v109
	v_and_b32_e32 v109, 0xffff0000, v109
	v_pk_add_f32 v[104:105], v[104:105], v[108:109]
	v_pk_add_f32 v[108:109], v[102:103], v[112:113]
	s_nop 0
	v_cvt_pk_bf16_f32 v102, v108, v109
	v_cvt_pk_bf16_f32 v103, v104, v105
	v_mul_f32_e32 v109, v109, v109
	v_mul_f32_e32 v105, v105, v105
	v_fmac_f32_e32 v109, v108, v108
	v_fmac_f32_e32 v105, v104, v104
	v_add_f32_e32 v104, v109, v105
	v_add_f32_e32 v112, v116, v104
	v_lshlrev_b32_e32 v104, 16, v110
	v_and_b32_e32 v105, 0xffff0000, v110
	v_lshlrev_b32_e32 v108, 16, v111
	v_and_b32_e32 v109, 0xffff0000, v111
	v_pk_add_f32 v[98:99], v[98:99], v[104:105]
	v_pk_add_f32 v[100:101], v[100:101], v[108:109]
	v_cvt_pk_bf16_f32 v104, v98, v99
	v_mul_f32_e32 v99, v99, v99
	v_fmac_f32_e32 v99, v98, v98
	v_mul_f32_e32 v98, v101, v101
	v_fmac_f32_e32 v98, v100, v100
	v_add_f32_e32 v98, v99, v98
	v_add_f32_e32 v98, v98, v112
	v_mov_b32_e32 v99, v98
	s_nop 1
	v_permlane16_swap_b32_e32 v98, v99
	v_add_f32_e32 v98, v98, v99
	v_mov_b32_e32 v99, v98
	s_nop 1
	v_permlane32_swap_b32_e32 v98, v99
	v_cvt_pk_bf16_f32 v105, v100, v101
	global_store_dwordx4 v[106:107], v[102:105], off offset:256
	s_and_saveexec_b64 s[12:13], s[40:41]
	s_cbranch_execz .LBB0_871
	v_lshlrev_b64 v[100:101], 6, v[114:115]
	v_lshl_add_u64 v[100:101], s[14:15], 0, v[100:101]
	v_lshl_add_u64 v[100:101], s[36:37], 2, v[100:101]
	s_lshl_b32 s0, s55, 2
	v_lshl_add_u64 v[100:101], v[100:101], 0, s[0:1]
	v_add_f32_e32 v98, v98, v99
	global_store_dword v[100:101], v98, off
.LBB0_871:
	s_or_b64 exec, exec, s[12:13]
	v_or_b32_e32 v98, 32, v142
	v_ashrrev_i32_e32 v99, 31, v98
	v_lshlrev_b64 v[100:101], 10, v[98:99]
	v_lshl_add_u64 v[100:101], v[100:101], 0, v[140:141]
	v_lshlrev_b64 v[104:105], 1, v[100:101]
	v_lshl_add_u64 v[106:107], s[6:7], 0, v[104:105]
	s_waitcnt vmcnt(15)
	v_mov_b32_e32 v100, v174
	v_mov_b32_e32 v101, v175
	v_mov_b32_e32 v102, v176
	v_mov_b32_e32 v103, v177
	v_lshlrev_b32_e32 v108, 16, v100
	v_and_b32_e32 v109, 0xffff0000, v100
	v_lshlrev_b32_e32 v100, 16, v101
	v_and_b32_e32 v101, 0xffff0000, v101
	v_pk_add_f32 v[96:97], v[96:97], v[100:101]
	v_pk_add_f32 v[100:101], v[94:95], v[108:109]
	s_nop 0
	v_cvt_pk_bf16_f32 v94, v100, v101
	v_cvt_pk_bf16_f32 v95, v96, v97
	v_mul_f32_e32 v101, v101, v101
	v_mul_f32_e32 v97, v97, v97
	v_fmac_f32_e32 v101, v100, v100
	v_fmac_f32_e32 v97, v96, v96
	v_add_f32_e32 v108, v101, v97
	v_lshlrev_b32_e32 v96, 16, v102
	v_and_b32_e32 v97, 0xffff0000, v102
	v_lshlrev_b32_e32 v100, 16, v103
	v_and_b32_e32 v101, 0xffff0000, v103
	v_pk_add_f32 v[90:91], v[90:91], v[96:97]
	v_pk_add_f32 v[92:93], v[92:93], v[100:101]
	v_cvt_pk_bf16_f32 v96, v90, v91
	v_mul_f32_e32 v91, v91, v91
	v_fmac_f32_e32 v91, v90, v90
	v_mul_f32_e32 v90, v93, v93
	v_fmac_f32_e32 v90, v92, v92
	v_add_f32_e32 v90, v91, v90
	v_add_f32_e32 v100, v108, v90
	v_lshl_add_u64 v[90:91], s[10:11], 0, v[104:105]
	v_cvt_pk_bf16_f32 v97, v92, v93
	global_store_dwordx4 v[90:91], v[94:97], off
	s_waitcnt vmcnt(15)
	v_mov_b32_e32 v92, v178
	v_mov_b32_e32 v93, v179
	v_mov_b32_e32 v94, v180
	v_mov_b32_e32 v95, v181
	v_lshlrev_b32_e32 v96, 16, v92
	v_and_b32_e32 v97, 0xffff0000, v92
	v_lshlrev_b32_e32 v92, 16, v93
	v_and_b32_e32 v93, 0xffff0000, v93
	v_pk_add_f32 v[88:89], v[88:89], v[92:93]
	v_pk_add_f32 v[92:93], v[86:87], v[96:97]
	s_nop 0
	v_cvt_pk_bf16_f32 v86, v92, v93
	v_cvt_pk_bf16_f32 v87, v88, v89
	v_mul_f32_e32 v93, v93, v93
	v_mul_f32_e32 v89, v89, v89
	v_fmac_f32_e32 v93, v92, v92
	v_fmac_f32_e32 v89, v88, v88
	v_add_f32_e32 v88, v93, v89
	v_add_f32_e32 v96, v100, v88
	v_lshlrev_b32_e32 v88, 16, v94
	v_and_b32_e32 v89, 0xffff0000, v94
	v_lshlrev_b32_e32 v92, 16, v95
	v_and_b32_e32 v93, 0xffff0000, v95
	v_pk_add_f32 v[82:83], v[82:83], v[88:89]
	v_pk_add_f32 v[84:85], v[84:85], v[92:93]
	v_cvt_pk_bf16_f32 v88, v82, v83
	v_mul_f32_e32 v83, v83, v83
	v_fmac_f32_e32 v83, v82, v82
	v_mul_f32_e32 v82, v85, v85
	v_fmac_f32_e32 v82, v84, v84
	v_add_f32_e32 v82, v83, v82
	v_add_f32_e32 v82, v82, v96
	v_mov_b32_e32 v83, v82
	s_nop 1
	v_permlane16_swap_b32_e32 v82, v83
	v_add_f32_e32 v82, v82, v83
	v_mov_b32_e32 v83, v82
	s_nop 1
	v_permlane32_swap_b32_e32 v82, v83
	v_cvt_pk_bf16_f32 v89, v84, v85
	global_store_dwordx4 v[90:91], v[86:89], off offset:256
	s_and_saveexec_b64 s[12:13], s[40:41]
	s_cbranch_execz .LBB0_873
	v_lshlrev_b64 v[84:85], 6, v[98:99]
	v_lshl_add_u64 v[84:85], s[14:15], 0, v[84:85]
	v_lshl_add_u64 v[84:85], s[36:37], 2, v[84:85]
	s_lshl_b32 s0, s55, 2
	v_lshl_add_u64 v[84:85], v[84:85], 0, s[0:1]
	v_add_f32_e32 v82, v82, v83
	global_store_dword v[84:85], v82, off
.LBB0_873:
	s_or_b64 exec, exec, s[12:13]
	v_or_b32_e32 v82, 48, v142
	v_ashrrev_i32_e32 v83, 31, v82
	v_lshlrev_b64 v[84:85], 10, v[82:83]
	v_lshl_add_u64 v[84:85], v[84:85], 0, v[140:141]
	v_lshlrev_b64 v[88:89], 1, v[84:85]
	v_lshl_add_u64 v[90:91], s[6:7], 0, v[88:89]
	s_waitcnt vmcnt(15)
	v_mov_b32_e32 v84, v184
	v_mov_b32_e32 v85, v185
	v_mov_b32_e32 v86, v186
	v_mov_b32_e32 v87, v187
	v_lshlrev_b32_e32 v92, 16, v84
	v_and_b32_e32 v93, 0xffff0000, v84
	v_lshlrev_b32_e32 v84, 16, v85
	v_and_b32_e32 v85, 0xffff0000, v85
	v_pk_add_f32 v[80:81], v[80:81], v[84:85]
	v_pk_add_f32 v[84:85], v[78:79], v[92:93]
	s_nop 0
	v_cvt_pk_bf16_f32 v78, v84, v85
	v_cvt_pk_bf16_f32 v79, v80, v81
	v_mul_f32_e32 v85, v85, v85
	v_mul_f32_e32 v81, v81, v81
	v_fmac_f32_e32 v85, v84, v84
	v_fmac_f32_e32 v81, v80, v80
	v_add_f32_e32 v92, v85, v81
	v_lshlrev_b32_e32 v80, 16, v86
	v_and_b32_e32 v81, 0xffff0000, v86
	v_lshlrev_b32_e32 v84, 16, v87
	v_and_b32_e32 v85, 0xffff0000, v87
	v_pk_add_f32 v[74:75], v[74:75], v[80:81]
	v_pk_add_f32 v[76:77], v[76:77], v[84:85]
	v_cvt_pk_bf16_f32 v80, v74, v75
	v_mul_f32_e32 v75, v75, v75
	v_fmac_f32_e32 v75, v74, v74
	v_mul_f32_e32 v74, v77, v77
	v_fmac_f32_e32 v74, v76, v76
	v_add_f32_e32 v74, v75, v74
	v_add_f32_e32 v84, v92, v74
	v_lshl_add_u64 v[74:75], s[10:11], 0, v[88:89]
	v_cvt_pk_bf16_f32 v81, v76, v77
	global_store_dwordx4 v[74:75], v[78:81], off
	s_waitcnt vmcnt(15)
	v_mov_b32_e32 v76, v188
	v_mov_b32_e32 v77, v189
	v_mov_b32_e32 v78, v190
	v_mov_b32_e32 v79, v191
	v_lshlrev_b32_e32 v80, 16, v76
	v_and_b32_e32 v81, 0xffff0000, v76
	v_lshlrev_b32_e32 v76, 16, v77
	v_and_b32_e32 v77, 0xffff0000, v77
	v_pk_add_f32 v[72:73], v[72:73], v[76:77]
	v_pk_add_f32 v[76:77], v[70:71], v[80:81]
	s_nop 0
	v_cvt_pk_bf16_f32 v70, v76, v77
	v_cvt_pk_bf16_f32 v71, v72, v73
	v_mul_f32_e32 v77, v77, v77
	v_mul_f32_e32 v73, v73, v73
	v_fmac_f32_e32 v77, v76, v76
	v_fmac_f32_e32 v73, v72, v72
	v_add_f32_e32 v72, v77, v73
	v_add_f32_e32 v80, v84, v72
	v_lshlrev_b32_e32 v72, 16, v78
	v_and_b32_e32 v73, 0xffff0000, v78
	v_lshlrev_b32_e32 v76, 16, v79
	v_and_b32_e32 v77, 0xffff0000, v79
	v_pk_add_f32 v[66:67], v[66:67], v[72:73]
	v_pk_add_f32 v[68:69], v[68:69], v[76:77]
	v_cvt_pk_bf16_f32 v72, v66, v67
	v_mul_f32_e32 v67, v67, v67
	v_fmac_f32_e32 v67, v66, v66
	v_mul_f32_e32 v66, v69, v69
	v_fmac_f32_e32 v66, v68, v68
	v_add_f32_e32 v66, v67, v66
	v_add_f32_e32 v66, v66, v80
	v_mov_b32_e32 v67, v66
	s_nop 1
	v_permlane16_swap_b32_e32 v66, v67
	v_add_f32_e32 v66, v66, v67
	v_mov_b32_e32 v67, v66
	s_nop 1
	v_permlane32_swap_b32_e32 v66, v67
	v_cvt_pk_bf16_f32 v73, v68, v69
	global_store_dwordx4 v[74:75], v[70:73], off offset:256
	s_and_saveexec_b64 s[12:13], s[40:41]
	s_cbranch_execz .LBB0_875
	v_lshlrev_b64 v[68:69], 6, v[82:83]
	v_lshl_add_u64 v[68:69], s[14:15], 0, v[68:69]
	v_lshl_add_u64 v[68:69], s[36:37], 2, v[68:69]
	s_lshl_b32 s0, s55, 2
	v_lshl_add_u64 v[68:69], v[68:69], 0, s[0:1]
	v_add_f32_e32 v66, v66, v67
	global_store_dword v[68:69], v66, off
.LBB0_875:
	s_or_b64 exec, exec, s[12:13]
	v_add_u32_e32 v66, 0x80, v142
	v_ashrrev_i32_e32 v67, 31, v66
	v_lshlrev_b64 v[68:69], 10, v[66:67]
	v_lshl_add_u64 v[68:69], v[68:69], 0, v[140:141]
	v_lshlrev_b64 v[72:73], 1, v[68:69]
	v_lshl_add_u64 v[74:75], s[6:7], 0, v[72:73]
	s_waitcnt vmcnt(15)
	v_mov_b32_e32 v68, v196
	v_mov_b32_e32 v69, v197
	v_mov_b32_e32 v70, v198
	v_mov_b32_e32 v71, v199
	v_lshlrev_b32_e32 v76, 16, v68
	v_and_b32_e32 v77, 0xffff0000, v68
	v_lshlrev_b32_e32 v68, 16, v69
	v_and_b32_e32 v69, 0xffff0000, v69
	v_pk_add_f32 v[64:65], v[64:65], v[68:69]
	v_pk_add_f32 v[68:69], v[62:63], v[76:77]
	s_nop 0
	v_cvt_pk_bf16_f32 v62, v68, v69
	v_cvt_pk_bf16_f32 v63, v64, v65
	v_mul_f32_e32 v69, v69, v69
	v_mul_f32_e32 v65, v65, v65
	v_fmac_f32_e32 v69, v68, v68
	v_fmac_f32_e32 v65, v64, v64
	v_add_f32_e32 v76, v69, v65
	v_lshlrev_b32_e32 v64, 16, v70
	v_and_b32_e32 v65, 0xffff0000, v70
	v_lshlrev_b32_e32 v68, 16, v71
	v_and_b32_e32 v69, 0xffff0000, v71
	v_pk_add_f32 v[58:59], v[58:59], v[64:65]
	v_pk_add_f32 v[60:61], v[60:61], v[68:69]
	v_cvt_pk_bf16_f32 v64, v58, v59
	v_mul_f32_e32 v59, v59, v59
	v_fmac_f32_e32 v59, v58, v58
	v_mul_f32_e32 v58, v61, v61
	v_fmac_f32_e32 v58, v60, v60
	v_add_f32_e32 v58, v59, v58
	v_add_f32_e32 v68, v76, v58
	v_lshl_add_u64 v[58:59], s[10:11], 0, v[72:73]
	v_cvt_pk_bf16_f32 v65, v60, v61
	global_store_dwordx4 v[58:59], v[62:65], off
	s_waitcnt vmcnt(15)
	v_mov_b32_e32 v60, v210
	v_mov_b32_e32 v61, v211
	v_mov_b32_e32 v62, v212
	v_mov_b32_e32 v63, v213
	v_lshlrev_b32_e32 v64, 16, v60
	v_and_b32_e32 v65, 0xffff0000, v60
	v_lshlrev_b32_e32 v60, 16, v61
	v_and_b32_e32 v61, 0xffff0000, v61
	v_pk_add_f32 v[56:57], v[56:57], v[60:61]
	v_pk_add_f32 v[60:61], v[54:55], v[64:65]
	s_nop 0
	v_cvt_pk_bf16_f32 v54, v60, v61
	v_cvt_pk_bf16_f32 v55, v56, v57
	v_mul_f32_e32 v61, v61, v61
	v_mul_f32_e32 v57, v57, v57
	v_fmac_f32_e32 v61, v60, v60
	v_fmac_f32_e32 v57, v56, v56
	v_add_f32_e32 v56, v61, v57
	v_add_f32_e32 v64, v68, v56
	v_lshlrev_b32_e32 v56, 16, v62
	v_and_b32_e32 v57, 0xffff0000, v62
	v_lshlrev_b32_e32 v60, 16, v63
	v_and_b32_e32 v61, 0xffff0000, v63
	v_pk_add_f32 v[50:51], v[50:51], v[56:57]
	v_pk_add_f32 v[52:53], v[52:53], v[60:61]
	v_cvt_pk_bf16_f32 v56, v50, v51
	v_mul_f32_e32 v51, v51, v51
	v_fmac_f32_e32 v51, v50, v50
	v_mul_f32_e32 v50, v53, v53
	v_fmac_f32_e32 v50, v52, v52
	v_add_f32_e32 v50, v51, v50
	v_add_f32_e32 v50, v50, v64
	v_mov_b32_e32 v51, v50
	s_nop 1
	v_permlane16_swap_b32_e32 v50, v51
	v_add_f32_e32 v50, v50, v51
	v_mov_b32_e32 v51, v50
	s_nop 1
	v_permlane32_swap_b32_e32 v50, v51
	v_cvt_pk_bf16_f32 v57, v52, v53
	global_store_dwordx4 v[58:59], v[54:57], off offset:256
	s_and_saveexec_b64 s[12:13], s[40:41]
	s_cbranch_execz .LBB0_877
	v_lshlrev_b64 v[52:53], 6, v[66:67]
	v_lshl_add_u64 v[52:53], s[14:15], 0, v[52:53]
	v_lshl_add_u64 v[52:53], s[36:37], 2, v[52:53]
	s_lshl_b32 s0, s55, 2
	v_lshl_add_u64 v[52:53], v[52:53], 0, s[0:1]
	v_add_f32_e32 v50, v50, v51
	global_store_dword v[52:53], v50, off
.LBB0_877:
	s_or_b64 exec, exec, s[12:13]
	v_add_u32_e32 v50, 0x90, v142
	v_ashrrev_i32_e32 v51, 31, v50
	v_lshlrev_b64 v[52:53], 10, v[50:51]
	v_lshl_add_u64 v[52:53], v[52:53], 0, v[140:141]
	v_lshlrev_b64 v[56:57], 1, v[52:53]
	v_lshl_add_u64 v[58:59], s[6:7], 0, v[56:57]
	s_waitcnt vmcnt(15)
	v_mov_b32_e32 v52, v214
	v_mov_b32_e32 v53, v215
	v_mov_b32_e32 v54, v216
	v_mov_b32_e32 v55, v217
	v_lshlrev_b32_e32 v60, 16, v52
	v_and_b32_e32 v61, 0xffff0000, v52
	v_lshlrev_b32_e32 v52, 16, v53
	v_and_b32_e32 v53, 0xffff0000, v53
	v_pk_add_f32 v[48:49], v[48:49], v[52:53]
	v_pk_add_f32 v[52:53], v[46:47], v[60:61]
	s_nop 0
	v_cvt_pk_bf16_f32 v46, v52, v53
	v_cvt_pk_bf16_f32 v47, v48, v49
	v_mul_f32_e32 v53, v53, v53
	v_mul_f32_e32 v49, v49, v49
	v_fmac_f32_e32 v53, v52, v52
	v_fmac_f32_e32 v49, v48, v48
	v_add_f32_e32 v60, v53, v49
	v_lshlrev_b32_e32 v48, 16, v54
	v_and_b32_e32 v49, 0xffff0000, v54
	v_lshlrev_b32_e32 v52, 16, v55
	v_and_b32_e32 v53, 0xffff0000, v55
	v_pk_add_f32 v[42:43], v[42:43], v[48:49]
	v_pk_add_f32 v[44:45], v[44:45], v[52:53]
	v_cvt_pk_bf16_f32 v48, v42, v43
	v_mul_f32_e32 v43, v43, v43
	v_fmac_f32_e32 v43, v42, v42
	v_mul_f32_e32 v42, v45, v45
	v_fmac_f32_e32 v42, v44, v44
	v_add_f32_e32 v42, v43, v42
	v_add_f32_e32 v52, v60, v42
	v_lshl_add_u64 v[42:43], s[10:11], 0, v[56:57]
	v_cvt_pk_bf16_f32 v49, v44, v45
	global_store_dwordx4 v[42:43], v[46:49], off
	s_waitcnt vmcnt(15)
	v_mov_b32_e32 v44, v218
	v_mov_b32_e32 v45, v219
	v_mov_b32_e32 v46, v220
	v_mov_b32_e32 v47, v221
	v_lshlrev_b32_e32 v48, 16, v44
	v_and_b32_e32 v49, 0xffff0000, v44
	v_lshlrev_b32_e32 v44, 16, v45
	v_and_b32_e32 v45, 0xffff0000, v45
	v_pk_add_f32 v[40:41], v[40:41], v[44:45]
	v_pk_add_f32 v[44:45], v[38:39], v[48:49]
	s_nop 0
	v_cvt_pk_bf16_f32 v38, v44, v45
	v_cvt_pk_bf16_f32 v39, v40, v41
	v_mul_f32_e32 v45, v45, v45
	v_mul_f32_e32 v41, v41, v41
	v_fmac_f32_e32 v45, v44, v44
	v_fmac_f32_e32 v41, v40, v40
	v_add_f32_e32 v40, v45, v41
	v_add_f32_e32 v48, v52, v40
	v_lshlrev_b32_e32 v40, 16, v46
	v_and_b32_e32 v41, 0xffff0000, v46
	v_lshlrev_b32_e32 v44, 16, v47
	v_and_b32_e32 v45, 0xffff0000, v47
	v_pk_add_f32 v[34:35], v[34:35], v[40:41]
	v_pk_add_f32 v[36:37], v[36:37], v[44:45]
	v_cvt_pk_bf16_f32 v40, v34, v35
	v_mul_f32_e32 v35, v35, v35
	v_fmac_f32_e32 v35, v34, v34
	v_mul_f32_e32 v34, v37, v37
	v_fmac_f32_e32 v34, v36, v36
	v_add_f32_e32 v34, v35, v34
	v_add_f32_e32 v34, v34, v48
	v_mov_b32_e32 v35, v34
	s_nop 1
	v_permlane16_swap_b32_e32 v34, v35
	v_add_f32_e32 v34, v34, v35
	v_mov_b32_e32 v35, v34
	s_nop 1
	v_permlane32_swap_b32_e32 v34, v35
	v_cvt_pk_bf16_f32 v41, v36, v37
	global_store_dwordx4 v[42:43], v[38:41], off offset:256
	s_and_saveexec_b64 s[12:13], s[40:41]
	s_cbranch_execz .LBB0_879
	v_lshlrev_b64 v[36:37], 6, v[50:51]
	v_lshl_add_u64 v[36:37], s[14:15], 0, v[36:37]
	v_lshl_add_u64 v[36:37], s[36:37], 2, v[36:37]
	s_lshl_b32 s0, s55, 2
	v_lshl_add_u64 v[36:37], v[36:37], 0, s[0:1]
	v_add_f32_e32 v34, v34, v35
	global_store_dword v[36:37], v34, off
.LBB0_879:
	s_or_b64 exec, exec, s[12:13]
	v_add_u32_e32 v34, 0xa0, v142
	v_ashrrev_i32_e32 v35, 31, v34
	v_lshlrev_b64 v[36:37], 10, v[34:35]
	v_lshl_add_u64 v[36:37], v[36:37], 0, v[140:141]
	v_lshlrev_b64 v[40:41], 1, v[36:37]
	v_lshl_add_u64 v[42:43], s[6:7], 0, v[40:41]
	s_waitcnt vmcnt(15)
	v_mov_b32_e32 v36, v222
	v_mov_b32_e32 v37, v223
	v_mov_b32_e32 v38, v224
	v_mov_b32_e32 v39, v225
	v_lshlrev_b32_e32 v44, 16, v36
	v_and_b32_e32 v45, 0xffff0000, v36
	v_lshlrev_b32_e32 v36, 16, v37
	v_and_b32_e32 v37, 0xffff0000, v37
	v_pk_add_f32 v[32:33], v[32:33], v[36:37]
	v_pk_add_f32 v[36:37], v[30:31], v[44:45]
	s_nop 0
	v_cvt_pk_bf16_f32 v30, v36, v37
	v_cvt_pk_bf16_f32 v31, v32, v33
	v_mul_f32_e32 v37, v37, v37
	v_mul_f32_e32 v33, v33, v33
	v_fmac_f32_e32 v37, v36, v36
	v_fmac_f32_e32 v33, v32, v32
	v_add_f32_e32 v44, v37, v33
	v_lshlrev_b32_e32 v32, 16, v38
	v_and_b32_e32 v33, 0xffff0000, v38
	v_lshlrev_b32_e32 v36, 16, v39
	v_and_b32_e32 v37, 0xffff0000, v39
	v_pk_add_f32 v[26:27], v[26:27], v[32:33]
	v_pk_add_f32 v[28:29], v[28:29], v[36:37]
	v_cvt_pk_bf16_f32 v32, v26, v27
	v_mul_f32_e32 v27, v27, v27
	v_fmac_f32_e32 v27, v26, v26
	v_mul_f32_e32 v26, v29, v29
	v_fmac_f32_e32 v26, v28, v28
	v_add_f32_e32 v26, v27, v26
	v_add_f32_e32 v36, v44, v26
	v_lshl_add_u64 v[26:27], s[10:11], 0, v[40:41]
	v_cvt_pk_bf16_f32 v33, v28, v29
	global_store_dwordx4 v[26:27], v[30:33], off
	s_waitcnt vmcnt(15)
	v_mov_b32_e32 v28, v226
	v_mov_b32_e32 v29, v227
	v_mov_b32_e32 v30, v228
	v_mov_b32_e32 v31, v229
	v_lshlrev_b32_e32 v32, 16, v28
	v_and_b32_e32 v33, 0xffff0000, v28
	v_lshlrev_b32_e32 v28, 16, v29
	v_and_b32_e32 v29, 0xffff0000, v29
	v_pk_add_f32 v[24:25], v[24:25], v[28:29]
	v_pk_add_f32 v[28:29], v[22:23], v[32:33]
	s_nop 0
	v_cvt_pk_bf16_f32 v22, v28, v29
	v_cvt_pk_bf16_f32 v23, v24, v25
	v_mul_f32_e32 v29, v29, v29
	v_mul_f32_e32 v25, v25, v25
	v_fmac_f32_e32 v29, v28, v28
	v_fmac_f32_e32 v25, v24, v24
	v_add_f32_e32 v24, v29, v25
	v_add_f32_e32 v32, v36, v24
	v_lshlrev_b32_e32 v24, 16, v30
	v_and_b32_e32 v25, 0xffff0000, v30
	v_lshlrev_b32_e32 v28, 16, v31
	v_and_b32_e32 v29, 0xffff0000, v31
	v_pk_add_f32 v[18:19], v[18:19], v[24:25]
	v_pk_add_f32 v[20:21], v[20:21], v[28:29]
	v_cvt_pk_bf16_f32 v24, v18, v19
	v_mul_f32_e32 v19, v19, v19
	v_fmac_f32_e32 v19, v18, v18
	v_mul_f32_e32 v18, v21, v21
	v_fmac_f32_e32 v18, v20, v20
	v_add_f32_e32 v18, v19, v18
	v_add_f32_e32 v18, v18, v32
	v_mov_b32_e32 v19, v18
	s_nop 1
	v_permlane16_swap_b32_e32 v18, v19
	v_add_f32_e32 v18, v18, v19
	v_mov_b32_e32 v19, v18
	s_nop 1
	v_permlane32_swap_b32_e32 v18, v19
	v_cvt_pk_bf16_f32 v25, v20, v21
	global_store_dwordx4 v[26:27], v[22:25], off offset:256
	s_and_saveexec_b64 s[12:13], s[40:41]
	s_cbranch_execz .LBB0_881
	v_lshlrev_b64 v[20:21], 6, v[34:35]
	v_lshl_add_u64 v[20:21], s[14:15], 0, v[20:21]
	v_lshl_add_u64 v[20:21], s[36:37], 2, v[20:21]
	s_lshl_b32 s0, s55, 2
	v_lshl_add_u64 v[20:21], v[20:21], 0, s[0:1]
	v_add_f32_e32 v18, v18, v19
	global_store_dword v[20:21], v18, off
.LBB0_881:
	s_or_b64 exec, exec, s[12:13]
	v_add_u32_e32 v18, 0xb0, v142
	v_ashrrev_i32_e32 v19, 31, v18
	v_lshlrev_b64 v[20:21], 10, v[18:19]
	v_lshl_add_u64 v[20:21], v[20:21], 0, v[140:141]
	v_lshlrev_b64 v[24:25], 1, v[20:21]
	v_lshl_add_u64 v[26:27], s[6:7], 0, v[24:25]
	s_waitcnt vmcnt(15)
	v_mov_b32_e32 v20, v230
	v_mov_b32_e32 v21, v231
	v_mov_b32_e32 v22, v232
	v_mov_b32_e32 v23, v233
	v_lshlrev_b32_e32 v28, 16, v20
	v_and_b32_e32 v29, 0xffff0000, v20
	v_lshlrev_b32_e32 v20, 16, v21
	v_and_b32_e32 v21, 0xffff0000, v21
	v_pk_add_f32 v[16:17], v[16:17], v[20:21]
	v_pk_add_f32 v[20:21], v[14:15], v[28:29]
	s_nop 0
	v_cvt_pk_bf16_f32 v14, v20, v21
	v_cvt_pk_bf16_f32 v15, v16, v17
	v_mul_f32_e32 v21, v21, v21
	v_mul_f32_e32 v17, v17, v17
	v_fmac_f32_e32 v21, v20, v20
	v_fmac_f32_e32 v17, v16, v16
	v_add_f32_e32 v28, v21, v17
	v_lshlrev_b32_e32 v16, 16, v22
	v_and_b32_e32 v17, 0xffff0000, v22
	v_lshlrev_b32_e32 v20, 16, v23
	v_and_b32_e32 v21, 0xffff0000, v23
	v_pk_add_f32 v[10:11], v[10:11], v[16:17]
	v_pk_add_f32 v[12:13], v[12:13], v[20:21]
	v_cvt_pk_bf16_f32 v16, v10, v11
	v_mul_f32_e32 v11, v11, v11
	v_fmac_f32_e32 v11, v10, v10
	v_mul_f32_e32 v10, v13, v13
	v_fmac_f32_e32 v10, v12, v12
	v_add_f32_e32 v10, v11, v10
	v_add_f32_e32 v20, v28, v10
	v_lshl_add_u64 v[10:11], s[10:11], 0, v[24:25]
	v_cvt_pk_bf16_f32 v17, v12, v13
	global_store_dwordx4 v[10:11], v[14:17], off
	s_waitcnt vmcnt(15)
	v_mov_b32_e32 v12, v234
	v_mov_b32_e32 v13, v235
	v_mov_b32_e32 v14, v236
	v_mov_b32_e32 v15, v237
	v_lshlrev_b32_e32 v16, 16, v12
	v_and_b32_e32 v17, 0xffff0000, v12
	v_lshlrev_b32_e32 v12, 16, v13
	v_and_b32_e32 v13, 0xffff0000, v13
	v_pk_add_f32 v[8:9], v[8:9], v[12:13]
	v_pk_add_f32 v[12:13], v[6:7], v[16:17]
	s_nop 0
	v_cvt_pk_bf16_f32 v6, v12, v13
	v_cvt_pk_bf16_f32 v7, v8, v9
	v_mul_f32_e32 v13, v13, v13
	v_mul_f32_e32 v9, v9, v9
	v_fmac_f32_e32 v13, v12, v12
	v_fmac_f32_e32 v9, v8, v8
	v_add_f32_e32 v8, v13, v9
	v_add_f32_e32 v16, v20, v8
	v_lshlrev_b32_e32 v8, 16, v14
	v_and_b32_e32 v9, 0xffff0000, v14
	v_lshlrev_b32_e32 v12, 16, v15
	v_and_b32_e32 v13, 0xffff0000, v15
	v_pk_add_f32 v[2:3], v[2:3], v[8:9]
	v_pk_add_f32 v[4:5], v[4:5], v[12:13]
	v_cvt_pk_bf16_f32 v8, v2, v3
	v_mul_f32_e32 v3, v3, v3
	v_fmac_f32_e32 v3, v2, v2
	v_mul_f32_e32 v2, v5, v5
	v_fmac_f32_e32 v2, v4, v4
	v_add_f32_e32 v2, v3, v2
	v_add_f32_e32 v2, v2, v16
	v_mov_b32_e32 v3, v2
	s_nop 1
	v_permlane16_swap_b32_e32 v2, v3
	v_add_f32_e32 v2, v2, v3
	v_mov_b32_e32 v3, v2
	s_nop 1
	v_permlane32_swap_b32_e32 v2, v3
	v_cvt_pk_bf16_f32 v9, v4, v5
	global_store_dwordx4 v[10:11], v[6:9], off offset:256
	s_and_saveexec_b64 s[12:13], s[40:41]
	s_cbranch_execz .LBB0_883
	v_lshlrev_b64 v[4:5], 6, v[18:19]
	v_lshl_add_u64 v[4:5], s[14:15], 0, v[4:5]
	v_lshl_add_u64 v[4:5], s[36:37], 2, v[4:5]
	s_lshl_b32 s0, s55, 2
	v_lshl_add_u64 v[4:5], v[4:5], 0, s[0:1]
	v_add_f32_e32 v2, v2, v3
	global_store_dword v[4:5], v2, off

.LBB0_989:
	s_lshl_b32 s3, s2, 2
	v_lshl_add_u32 v142, s2, 8, v146
	v_lshl_or_b32 v140, s57, 8, v148
	s_add_i32 s12, s3, s57
	v_ashrrev_i32_e32 v143, 31, v142
	v_ashrrev_i32_e32 v141, 31, v140
	v_lshlrev_b64 v[144:145], 10, v[142:143]
	s_ashr_i32 s13, s12, 31
	v_mov_b32_e32 v151, v195
	v_lshl_add_u64 v[144:145], v[144:145], 0, v[140:141]
	s_lshl_b64 s[2:3], s[12:13], 17
	v_lshlrev_b64 v[160:161], 1, v[144:145]
	s_add_u32 s2, s52, s2
	v_lshlrev_b32_e32 v144, 1, v151
	s_addc_u32 s3, s53, s3
	v_ashrrev_i32_e32 v145, 31, v144
	v_lshl_add_u64 v[162:163], s[6:7], 0, v[160:161]
	v_lshl_add_u64 v[144:145], v[144:145], 4, s[2:3]
	global_load_dwordx4 v[172:175], v[162:163], off
	global_load_dwordx4 v[176:179], v[162:163], off offset:256
	s_mov_b64 s[100:101], 0x8000
	v_lshl_add_u64 v[180:181], v[162:163], 0, s[100:101]
	global_load_dwordx4 v[184:187], v[180:181], off
	global_load_dwordx4 v[188:191], v[180:181], off offset:256
	s_mov_b64 s[100:101], 0x8000
	v_lshl_add_u64 v[180:181], v[180:181], 0, s[100:101]
	global_load_dwordx4 v[196:199], v[180:181], off
	global_load_dwordx4 v[210:213], v[180:181], off offset:256
	s_mov_b64 s[100:101], 0x8000
	v_lshl_add_u64 v[180:181], v[180:181], 0, s[100:101]
	global_load_dwordx4 v[214:217], v[180:181], off
	global_load_dwordx4 v[218:221], v[180:181], off offset:256
	s_mov_b64 s[100:101], 0x28000
	v_lshl_add_u64 v[180:181], v[180:181], 0, s[100:101]
	global_load_dwordx4 v[222:225], v[180:181], off
	global_load_dwordx4 v[226:229], v[180:181], off offset:256
	s_mov_b64 s[100:101], 0x8000
	v_lshl_add_u64 v[180:181], v[180:181], 0, s[100:101]
	global_load_dwordx4 v[230:233], v[180:181], off
	global_load_dwordx4 v[234:237], v[180:181], off offset:256
	s_mov_b64 s[100:101], 0x8000
	v_lshl_add_u64 v[180:181], v[180:181], 0, s[100:101]
	global_load_dwordx4 v[238:241], v[180:181], off
	global_load_dwordx4 v[242:245], v[180:181], off offset:256
	s_mov_b64 s[100:101], 0x8000
	v_lshl_add_u64 v[180:181], v[180:181], 0, s[100:101]
	global_load_dwordx4 v[246:249], v[180:181], off
	global_load_dwordx4 v[156:159], v[144:145], off
	s_lshl_b32 s15, s0, 10
	s_add_i32 s15, s15, 0x20400
	v_lshl_or_b32 v151, v149, 2, s15
	ds_read_b32 v151, v151
	v_lshl_add_u64 v[160:161], s[74:75], 0, v[160:161]
	s_waitcnt lgkmcnt(0)
	v_mul_f32_e32 v151, 0xbfb8aa3b, v151
	v_mul_f32_e32 v126, v126, v151
	v_mul_f32_e32 v127, v127, v151
	v_mul_f32_e32 v128, v128, v151
	v_mul_f32_e32 v129, v129, v151
	v_mul_f32_e32 v122, v122, v151
	v_mul_f32_e32 v123, v123, v151
	v_mul_f32_e32 v124, v124, v151
	v_mul_f32_e32 v125, v125, v151
	v_exp_f32_e32 v126, v126
	v_exp_f32_e32 v127, v127
	v_exp_f32_e32 v128, v128
	v_exp_f32_e32 v129, v129
	v_exp_f32_e32 v122, v122
	v_exp_f32_e32 v123, v123
	v_exp_f32_e32 v124, v124
	v_exp_f32_e32 v125, v125
	v_add_f32_e32 v126, 1.0, v126
	v_add_f32_e32 v127, 1.0, v127
	v_add_f32_e32 v128, 1.0, v128
	v_add_f32_e32 v129, 1.0, v129
	v_add_f32_e32 v164, 1.0, v122
	v_add_f32_e32 v165, 1.0, v123
	v_add_f32_e32 v166, 1.0, v124
	v_add_f32_e32 v167, 1.0, v125
	v_rcp_f32_e32 v122, v126
	v_rcp_f32_e32 v123, v127
	v_rcp_f32_e32 v124, v128
	v_rcp_f32_e32 v125, v129
	v_rcp_f32_e32 v126, v164
	v_rcp_f32_e32 v127, v165
	v_rcp_f32_e32 v128, v166
	v_rcp_f32_e32 v129, v167
	v_mul_f32_e32 v118, v118, v151
	v_mul_f32_e32 v119, v119, v151
	v_mul_f32_e32 v120, v120, v151
	v_mul_f32_e32 v121, v121, v151
	v_mul_f32_e32 v114, v114, v151
	v_mul_f32_e32 v115, v115, v151
	v_mul_f32_e32 v116, v116, v151
	v_mul_f32_e32 v117, v117, v151
	v_exp_f32_e32 v118, v118
	v_exp_f32_e32 v119, v119
	v_exp_f32_e32 v120, v120
	v_exp_f32_e32 v121, v121
	v_exp_f32_e32 v114, v114
	v_exp_f32_e32 v115, v115
	v_exp_f32_e32 v116, v116
	v_exp_f32_e32 v117, v117
	v_add_f32_e32 v118, 1.0, v118
	v_add_f32_e32 v119, 1.0, v119
	v_add_f32_e32 v120, 1.0, v120
	v_add_f32_e32 v121, 1.0, v121
	v_add_f32_e32 v151, 1.0, v114
	v_rcp_f32_e32 v114, v118
	v_rcp_f32_e32 v118, v151
	s_waitcnt vmcnt(0)
	v_mov_b32_e32 v152, v172
	v_mov_b32_e32 v153, v173
	v_mov_b32_e32 v154, v174
	v_mov_b32_e32 v155, v175
	v_lshlrev_b32_e32 v164, 16, v152
	v_and_b32_e32 v165, 0xffff0000, v152
	v_lshlrev_b32_e32 v152, 16, v153
	v_and_b32_e32 v153, 0xffff0000, v153
	v_lshlrev_b32_e32 v166, 16, v154
	v_and_b32_e32 v167, 0xffff0000, v154
	v_lshlrev_b32_e32 v154, 16, v155
	v_and_b32_e32 v155, 0xffff0000, v155
	v_lshlrev_b32_e32 v168, 16, v156
	v_and_b32_e32 v169, 0xffff0000, v156
	v_lshlrev_b32_e32 v156, 16, v157
	v_and_b32_e32 v157, 0xffff0000, v157
	v_lshlrev_b32_e32 v170, 16, v158
	v_and_b32_e32 v171, 0xffff0000, v158
	v_lshlrev_b32_e32 v158, 16, v159
	v_and_b32_e32 v159, 0xffff0000, v159
	v_pk_fma_f32 v[152:153], v[124:125], v[156:157], v[152:153]
	v_pk_fma_f32 v[156:157], v[122:123], v[168:169], v[164:165]
	v_pk_fma_f32 v[154:155], v[128:129], v[158:159], v[154:155]
	v_pk_fma_f32 v[158:159], v[126:127], v[170:171], v[166:167]
	v_cvt_pk_bf16_f32 v122, v156, v157
	v_cvt_pk_bf16_f32 v123, v152, v153
	v_add_f32_e32 v164, 1.0, v117
	v_cvt_pk_bf16_f32 v124, v158, v159
	v_cvt_pk_bf16_f32 v125, v154, v155
	global_store_dwordx4 v[160:161], v[122:125], off
	s_nop 0
	global_load_dwordx4 v[126:129], v[144:145], off offset:16
	v_add_f32_e32 v162, 1.0, v115
	v_add_f32_e32 v163, 1.0, v116
	v_rcp_f32_e32 v115, v119
	v_rcp_f32_e32 v116, v120
	v_rcp_f32_e32 v117, v121
	v_mul_f32_e32 v151, v157, v157
	v_mul_f32_e32 v153, v153, v153
	v_mul_f32_e32 v157, v159, v159
	v_mul_f32_e32 v155, v155, v155
	v_rcp_f32_e32 v119, v162
	v_rcp_f32_e32 v120, v163
	v_rcp_f32_e32 v121, v164
	v_fmac_f32_e32 v151, v156, v156
	v_fmac_f32_e32 v153, v152, v152
	v_fmac_f32_e32 v157, v158, v158
	v_fmac_f32_e32 v155, v154, v154
	v_add_f32_e32 v151, v151, v153
	v_add_f32_e32 v152, v157, v155
	v_add_f32_e32 v151, v151, v152
	s_waitcnt vmcnt(1)
	v_mov_b32_e32 v122, v176
	v_mov_b32_e32 v123, v177
	v_mov_b32_e32 v124, v178
	v_mov_b32_e32 v125, v179
	v_lshlrev_b32_e32 v152, 16, v122
	v_and_b32_e32 v153, 0xffff0000, v122
	v_lshlrev_b32_e32 v122, 16, v123
	v_and_b32_e32 v123, 0xffff0000, v123
	s_waitcnt vmcnt(0)
	v_lshlrev_b32_e32 v154, 16, v126
	v_and_b32_e32 v155, 0xffff0000, v126
	v_lshlrev_b32_e32 v126, 16, v127
	v_and_b32_e32 v127, 0xffff0000, v127
	v_lshlrev_b32_e32 v156, 16, v124
	v_and_b32_e32 v157, 0xffff0000, v124
	v_lshlrev_b32_e32 v124, 16, v125
	v_and_b32_e32 v125, 0xffff0000, v125
	v_lshlrev_b32_e32 v158, 16, v128
	v_and_b32_e32 v159, 0xffff0000, v128
	v_lshlrev_b32_e32 v128, 16, v129
	v_and_b32_e32 v129, 0xffff0000, v129
	v_pk_fma_f32 v[122:123], v[116:117], v[126:127], v[122:123]
	v_pk_fma_f32 v[126:127], v[114:115], v[154:155], v[152:153]
	v_pk_fma_f32 v[120:121], v[120:121], v[128:129], v[124:125]
	v_pk_fma_f32 v[118:119], v[118:119], v[158:159], v[156:157]
	v_cvt_pk_bf16_f32 v114, v126, v127
	v_cvt_pk_bf16_f32 v115, v122, v123
	v_mul_f32_e32 v124, v127, v127
	v_mul_f32_e32 v123, v123, v123
	v_cvt_pk_bf16_f32 v116, v118, v119
	v_cvt_pk_bf16_f32 v117, v120, v121
	v_mul_f32_e32 v119, v119, v119
	v_mul_f32_e32 v121, v121, v121
	v_fmac_f32_e32 v124, v126, v126
	v_fmac_f32_e32 v123, v122, v122
	v_fmac_f32_e32 v119, v118, v118
	v_fmac_f32_e32 v121, v120, v120
	global_store_dwordx4 v[160:161], v[114:117], off offset:256
	s_nop 1
	v_add_f32_e32 v114, v124, v123
	v_add_f32_e32 v115, v119, v121
	v_add_f32_e32 v114, v151, v114
	v_add_f32_e32 v114, v115, v114
	v_mov_b32_e32 v115, v114
	s_nop 1
	v_permlane16_swap_b32_e32 v114, v115
	v_add_f32_e32 v114, v114, v115
	v_mov_b32_e32 v115, v114
	s_nop 1
	v_permlane32_swap_b32_e32 v114, v115
	s_and_saveexec_b64 s[12:13], s[38:39]
	s_cbranch_execz .LBB0_991
	v_add_f32_e32 v116, v114, v115
	s_lshl_b32 s2, s57, 2
	v_lshlrev_b64 v[114:115], 6, v[142:143]
	s_ashr_i32 s3, s2, 31
	v_lshl_add_u64 v[114:115], s[8:9], 0, v[114:115]
	v_lshl_add_u64 v[114:115], s[2:3], 2, v[114:115]
	s_lshl_b32 s0, s51, 2
	v_lshl_add_u64 v[114:115], v[114:115], 0, s[0:1]
	global_store_dword v[114:115], v116, off
.LBB0_991:
	s_or_b64 exec, exec, s[12:13]
	v_bitop3_b32 v120, v142, s83, 16 bitop3:0xc8
	v_lshl_add_u64 v[114:115], v[144:145], 0, s[70:71]
	v_lshl_add_u32 v120, v120, 2, s15
	v_or_b32_e32 v116, 16, v142
	ds_read_b32 v120, v120
	v_ashrrev_i32_e32 v117, 31, v116
	v_lshlrev_b64 v[118:119], 10, v[116:117]
	v_lshl_add_u64 v[118:119], v[118:119], 0, v[140:141]
	v_lshlrev_b64 v[118:119], 1, v[118:119]
	s_waitcnt lgkmcnt(0)
	v_mul_f32_e32 v122, 0xbfb8aa3b, v120
	v_lshl_add_u64 v[120:121], s[6:7], 0, v[118:119]
	global_load_dwordx4 v[124:127], v[114:115], off
	v_mul_f32_e32 v110, v110, v122
	v_mul_f32_e32 v111, v111, v122
	v_mul_f32_e32 v112, v112, v122
	v_mul_f32_e32 v113, v113, v122
	v_exp_f32_e32 v110, v110
	v_exp_f32_e32 v111, v111
	v_exp_f32_e32 v112, v112
	v_exp_f32_e32 v113, v113
	v_mul_f32_e32 v106, v106, v122
	v_mul_f32_e32 v107, v107, v122
	v_add_f32_e32 v110, 1.0, v110
	v_add_f32_e32 v111, 1.0, v111
	v_add_f32_e32 v112, 1.0, v112
	v_add_f32_e32 v113, 1.0, v113
	v_exp_f32_e32 v106, v106
	v_exp_f32_e32 v107, v107
	v_mul_f32_e32 v108, v108, v122
	v_mul_f32_e32 v109, v109, v122
	v_rcp_f32_e32 v110, v110
	v_rcp_f32_e32 v111, v111
	v_rcp_f32_e32 v112, v112
	v_rcp_f32_e32 v113, v113
	v_exp_f32_e32 v108, v108
	v_exp_f32_e32 v109, v109
	v_add_f32_e32 v106, 1.0, v106
	v_add_f32_e32 v107, 1.0, v107
	v_rcp_f32_e32 v106, v106
	v_rcp_f32_e32 v107, v107
	v_add_f32_e32 v108, 1.0, v108
	v_add_f32_e32 v109, 1.0, v109
	v_rcp_f32_e32 v108, v108
	v_rcp_f32_e32 v109, v109
	v_lshl_add_u64 v[118:119], s[74:75], 0, v[118:119]
	v_mul_f32_e32 v102, v102, v122
	v_mul_f32_e32 v103, v103, v122
	v_mul_f32_e32 v104, v104, v122
	v_mul_f32_e32 v105, v105, v122
	v_exp_f32_e32 v102, v102
	v_exp_f32_e32 v103, v103
	v_exp_f32_e32 v104, v104
	v_exp_f32_e32 v105, v105
	v_add_f32_e32 v102, 1.0, v102
	v_add_f32_e32 v103, 1.0, v103
	v_add_f32_e32 v104, 1.0, v104
	v_add_f32_e32 v105, 1.0, v105
	v_mul_f32_e32 v98, v98, v122
	v_mul_f32_e32 v99, v99, v122
	v_rcp_f32_e32 v102, v102
	v_rcp_f32_e32 v103, v103
	v_rcp_f32_e32 v104, v104
	v_rcp_f32_e32 v105, v105
	v_exp_f32_e32 v98, v98
	v_exp_f32_e32 v99, v99
	v_mul_f32_e32 v100, v100, v122
	v_mul_f32_e32 v101, v101, v122
	v_exp_f32_e32 v100, v100
	v_exp_f32_e32 v101, v101
	v_add_f32_e32 v98, 1.0, v98
	v_add_f32_e32 v99, 1.0, v99
	v_rcp_f32_e32 v98, v98
	v_rcp_f32_e32 v99, v99
	v_add_f32_e32 v100, 1.0, v100
	v_add_f32_e32 v101, 1.0, v101
	v_rcp_f32_e32 v100, v100
	v_rcp_f32_e32 v101, v101
	s_waitcnt vmcnt(0)
	v_mov_b32_e32 v152, v184
	v_mov_b32_e32 v153, v185
	v_mov_b32_e32 v154, v186
	v_mov_b32_e32 v155, v187
	v_lshlrev_b32_e32 v128, 16, v152
	v_and_b32_e32 v129, 0xffff0000, v152
	v_lshlrev_b32_e32 v144, 16, v153
	v_and_b32_e32 v145, 0xffff0000, v153
	v_lshlrev_b32_e32 v152, 16, v124
	v_and_b32_e32 v153, 0xffff0000, v124
	v_lshlrev_b32_e32 v124, 16, v125
	v_and_b32_e32 v125, 0xffff0000, v125
	v_pk_fma_f32 v[112:113], v[112:113], v[124:125], v[144:145]
	v_pk_fma_f32 v[124:125], v[110:111], v[152:153], v[128:129]
	v_lshlrev_b32_e32 v128, 16, v126
	v_cvt_pk_bf16_f32 v110, v124, v125
	v_cvt_pk_bf16_f32 v111, v112, v113
	v_mul_f32_e32 v123, v125, v125
	v_mul_f32_e32 v113, v113, v113
	v_fmac_f32_e32 v123, v124, v124
	v_fmac_f32_e32 v113, v112, v112
	v_add_f32_e32 v123, v123, v113
	v_lshlrev_b32_e32 v112, 16, v154
	v_and_b32_e32 v113, 0xffff0000, v154
	v_and_b32_e32 v129, 0xffff0000, v126
	v_lshlrev_b32_e32 v124, 16, v155
	v_and_b32_e32 v125, 0xffff0000, v155
	v_lshlrev_b32_e32 v126, 16, v127
	v_and_b32_e32 v127, 0xffff0000, v127
	v_pk_fma_f32 v[106:107], v[106:107], v[128:129], v[112:113]
	v_pk_fma_f32 v[108:109], v[108:109], v[126:127], v[124:125]
	v_cvt_pk_bf16_f32 v112, v106, v107
	v_mul_f32_e32 v107, v107, v107
	v_fmac_f32_e32 v107, v106, v106
	v_mul_f32_e32 v106, v109, v109
	v_fmac_f32_e32 v106, v108, v108
	v_cvt_pk_bf16_f32 v113, v108, v109
	v_add_f32_e32 v106, v107, v106
	global_store_dwordx4 v[118:119], v[110:113], off
	v_add_f32_e32 v123, v123, v106
	global_load_dwordx4 v[106:109], v[114:115], off offset:16
	s_waitcnt vmcnt(1)
	v_mov_b32_e32 v110, v188
	v_mov_b32_e32 v111, v189
	v_mov_b32_e32 v112, v190
	v_mov_b32_e32 v113, v191
	v_lshlrev_b32_e32 v120, 16, v110
	v_and_b32_e32 v121, 0xffff0000, v110
	v_lshlrev_b32_e32 v110, 16, v111
	v_and_b32_e32 v111, 0xffff0000, v111
	s_waitcnt vmcnt(0)
	v_lshlrev_b32_e32 v124, 16, v106
	v_and_b32_e32 v125, 0xffff0000, v106
	v_lshlrev_b32_e32 v106, 16, v107
	v_and_b32_e32 v107, 0xffff0000, v107
	v_pk_fma_f32 v[104:105], v[104:105], v[106:107], v[110:111]
	v_pk_fma_f32 v[106:107], v[102:103], v[124:125], v[120:121]
	v_lshlrev_b32_e32 v110, 16, v108
	v_cvt_pk_bf16_f32 v102, v106, v107
	v_cvt_pk_bf16_f32 v103, v104, v105
	v_mul_f32_e32 v107, v107, v107
	v_mul_f32_e32 v105, v105, v105
	v_fmac_f32_e32 v107, v106, v106
	v_fmac_f32_e32 v105, v104, v104
	v_add_f32_e32 v104, v107, v105
	v_add_f32_e32 v120, v123, v104
	v_lshlrev_b32_e32 v104, 16, v112
	v_and_b32_e32 v105, 0xffff0000, v112
	v_and_b32_e32 v111, 0xffff0000, v108
	v_lshlrev_b32_e32 v106, 16, v113
	v_and_b32_e32 v107, 0xffff0000, v113
	v_lshlrev_b32_e32 v108, 16, v109
	v_and_b32_e32 v109, 0xffff0000, v109
	v_pk_fma_f32 v[98:99], v[98:99], v[110:111], v[104:105]
	v_pk_fma_f32 v[100:101], v[100:101], v[108:109], v[106:107]
	v_cvt_pk_bf16_f32 v104, v98, v99
	v_mul_f32_e32 v99, v99, v99
	v_fmac_f32_e32 v99, v98, v98
	v_mul_f32_e32 v98, v101, v101
	v_fmac_f32_e32 v98, v100, v100
	v_add_f32_e32 v98, v99, v98
	v_add_f32_e32 v98, v98, v120
	v_mov_b32_e32 v99, v98
	s_nop 1
	v_permlane16_swap_b32_e32 v98, v99
	v_add_f32_e32 v98, v98, v99
	v_mov_b32_e32 v99, v98
	s_nop 1
	v_permlane32_swap_b32_e32 v98, v99
	v_cvt_pk_bf16_f32 v105, v100, v101
	global_store_dwordx4 v[118:119], v[102:105], off offset:256
	s_and_saveexec_b64 s[12:13], s[38:39]
	s_cbranch_execz .LBB0_993
	v_add_f32_e32 v100, v98, v99
	s_lshl_b32 s2, s57, 2
	v_lshlrev_b64 v[98:99], 6, v[116:117]
	s_ashr_i32 s3, s2, 31
	v_lshl_add_u64 v[98:99], s[8:9], 0, v[98:99]
	v_lshl_add_u64 v[98:99], s[2:3], 2, v[98:99]
	s_lshl_b32 s0, s51, 2
	v_lshl_add_u64 v[98:99], v[98:99], 0, s[0:1]
	global_store_dword v[98:99], v100, off
.LBB0_993:
	s_or_b64 exec, exec, s[12:13]
	v_lshl_add_u64 v[98:99], v[114:115], 0, s[70:71]
	v_bitop3_b32 v104, v142, s95, 32 bitop3:0xc8
	v_lshl_add_u32 v104, v104, 2, s15
	v_or_b32_e32 v100, 32, v142
	ds_read_b32 v104, v104
	v_ashrrev_i32_e32 v101, 31, v100
	v_lshlrev_b64 v[102:103], 10, v[100:101]
	v_lshl_add_u64 v[102:103], v[102:103], 0, v[140:141]
	v_lshlrev_b64 v[102:103], 1, v[102:103]
	s_waitcnt lgkmcnt(0)
	v_mul_f32_e32 v106, 0xbfb8aa3b, v104
	v_lshl_add_u64 v[104:105], s[6:7], 0, v[102:103]
	global_load_dwordx4 v[112:115], v[98:99], off
	v_mul_f32_e32 v94, v94, v106
	v_mul_f32_e32 v95, v95, v106
	v_mul_f32_e32 v96, v96, v106
	v_mul_f32_e32 v97, v97, v106
	v_exp_f32_e32 v94, v94
	v_exp_f32_e32 v95, v95
	v_exp_f32_e32 v96, v96
	v_exp_f32_e32 v97, v97
	v_mul_f32_e32 v90, v90, v106
	v_mul_f32_e32 v91, v91, v106
	v_add_f32_e32 v94, 1.0, v94
	v_add_f32_e32 v95, 1.0, v95
	v_add_f32_e32 v96, 1.0, v96
	v_add_f32_e32 v97, 1.0, v97
	v_exp_f32_e32 v90, v90
	v_exp_f32_e32 v91, v91
	v_mul_f32_e32 v92, v92, v106
	v_mul_f32_e32 v93, v93, v106
	v_rcp_f32_e32 v94, v94
	v_rcp_f32_e32 v95, v95
	v_rcp_f32_e32 v96, v96
	v_rcp_f32_e32 v97, v97
	v_exp_f32_e32 v92, v92
	v_exp_f32_e32 v93, v93
	v_add_f32_e32 v90, 1.0, v90
	v_add_f32_e32 v91, 1.0, v91
	v_rcp_f32_e32 v90, v90
	v_rcp_f32_e32 v91, v91
	v_add_f32_e32 v92, 1.0, v92
	v_add_f32_e32 v93, 1.0, v93
	v_rcp_f32_e32 v92, v92
	v_rcp_f32_e32 v93, v93
	v_lshl_add_u64 v[102:103], s[74:75], 0, v[102:103]
	v_mul_f32_e32 v86, v86, v106
	v_mul_f32_e32 v87, v87, v106
	v_mul_f32_e32 v88, v88, v106
	v_mul_f32_e32 v89, v89, v106
	v_exp_f32_e32 v86, v86
	v_exp_f32_e32 v87, v87
	v_exp_f32_e32 v88, v88
	v_exp_f32_e32 v89, v89
	v_add_f32_e32 v86, 1.0, v86
	v_add_f32_e32 v87, 1.0, v87
	v_add_f32_e32 v88, 1.0, v88
	v_add_f32_e32 v89, 1.0, v89
	v_mul_f32_e32 v82, v82, v106
	v_mul_f32_e32 v83, v83, v106
	v_rcp_f32_e32 v86, v86
	v_rcp_f32_e32 v87, v87
	v_rcp_f32_e32 v88, v88
	v_rcp_f32_e32 v89, v89
	v_exp_f32_e32 v82, v82
	v_exp_f32_e32 v83, v83
	v_mul_f32_e32 v84, v84, v106
	v_mul_f32_e32 v85, v85, v106
	v_exp_f32_e32 v84, v84
	v_exp_f32_e32 v85, v85
	v_add_f32_e32 v82, 1.0, v82
	v_add_f32_e32 v83, 1.0, v83
	v_rcp_f32_e32 v82, v82
	v_rcp_f32_e32 v83, v83
	v_add_f32_e32 v84, 1.0, v84
	v_add_f32_e32 v85, 1.0, v85
	v_rcp_f32_e32 v84, v84
	v_rcp_f32_e32 v85, v85
	s_waitcnt vmcnt(1)
	v_mov_b32_e32 v108, v196
	v_mov_b32_e32 v109, v197
	v_mov_b32_e32 v110, v198
	v_mov_b32_e32 v111, v199
	v_lshlrev_b32_e32 v116, 16, v108
	v_and_b32_e32 v117, 0xffff0000, v108
	v_lshlrev_b32_e32 v108, 16, v109
	v_and_b32_e32 v109, 0xffff0000, v109
	s_waitcnt vmcnt(0)
	v_lshlrev_b32_e32 v118, 16, v112
	v_and_b32_e32 v119, 0xffff0000, v112
	v_lshlrev_b32_e32 v112, 16, v113
	v_and_b32_e32 v113, 0xffff0000, v113
	v_pk_fma_f32 v[96:97], v[96:97], v[112:113], v[108:109]
	v_pk_fma_f32 v[108:109], v[94:95], v[118:119], v[116:117]
	v_lshlrev_b32_e32 v112, 16, v115
	v_cvt_pk_bf16_f32 v94, v108, v109
	v_cvt_pk_bf16_f32 v95, v96, v97
	v_mul_f32_e32 v107, v109, v109
	v_mul_f32_e32 v97, v97, v97
	v_fmac_f32_e32 v107, v108, v108
	v_fmac_f32_e32 v97, v96, v96
	v_add_f32_e32 v107, v107, v97
	v_lshlrev_b32_e32 v96, 16, v110
	v_and_b32_e32 v97, 0xffff0000, v110
	v_lshlrev_b32_e32 v108, 16, v111
	v_and_b32_e32 v109, 0xffff0000, v111
	v_lshlrev_b32_e32 v110, 16, v114
	v_and_b32_e32 v111, 0xffff0000, v114
	v_and_b32_e32 v113, 0xffff0000, v115
	v_pk_fma_f32 v[90:91], v[90:91], v[110:111], v[96:97]
	v_pk_fma_f32 v[92:93], v[92:93], v[112:113], v[108:109]
	v_cvt_pk_bf16_f32 v96, v90, v91
	v_mul_f32_e32 v91, v91, v91
	v_fmac_f32_e32 v91, v90, v90
	v_mul_f32_e32 v90, v93, v93
	v_fmac_f32_e32 v90, v92, v92
	v_cvt_pk_bf16_f32 v97, v92, v93
	v_add_f32_e32 v90, v91, v90
	global_store_dwordx4 v[102:103], v[94:97], off
	v_add_f32_e32 v107, v107, v90
	global_load_dwordx4 v[90:93], v[98:99], off offset:16
	s_waitcnt vmcnt(1)
	v_mov_b32_e32 v94, v210
	v_mov_b32_e32 v95, v211
	v_mov_b32_e32 v96, v212
	v_mov_b32_e32 v97, v213
	v_lshlrev_b32_e32 v104, 16, v94
	v_and_b32_e32 v105, 0xffff0000, v94
	v_lshlrev_b32_e32 v94, 16, v95
	v_and_b32_e32 v95, 0xffff0000, v95
	s_waitcnt vmcnt(0)
	v_lshlrev_b32_e32 v108, 16, v90
	v_and_b32_e32 v109, 0xffff0000, v90
	v_lshlrev_b32_e32 v90, 16, v91
	v_and_b32_e32 v91, 0xffff0000, v91
	v_pk_fma_f32 v[88:89], v[88:89], v[90:91], v[94:95]
	v_pk_fma_f32 v[90:91], v[86:87], v[108:109], v[104:105]
	v_lshlrev_b32_e32 v94, 16, v92
	v_cvt_pk_bf16_f32 v86, v90, v91
	v_cvt_pk_bf16_f32 v87, v88, v89
	v_mul_f32_e32 v91, v91, v91
	v_mul_f32_e32 v89, v89, v89
	v_fmac_f32_e32 v91, v90, v90
	v_fmac_f32_e32 v89, v88, v88
	v_add_f32_e32 v88, v91, v89
	v_add_f32_e32 v104, v107, v88
	v_lshlrev_b32_e32 v88, 16, v96
	v_and_b32_e32 v89, 0xffff0000, v96
	v_and_b32_e32 v95, 0xffff0000, v92
	v_lshlrev_b32_e32 v90, 16, v97
	v_and_b32_e32 v91, 0xffff0000, v97
	v_lshlrev_b32_e32 v92, 16, v93
	v_and_b32_e32 v93, 0xffff0000, v93
	v_pk_fma_f32 v[82:83], v[82:83], v[94:95], v[88:89]
	v_pk_fma_f32 v[84:85], v[84:85], v[92:93], v[90:91]
	v_cvt_pk_bf16_f32 v88, v82, v83
	v_mul_f32_e32 v83, v83, v83
	v_fmac_f32_e32 v83, v82, v82
	v_mul_f32_e32 v82, v85, v85
	v_fmac_f32_e32 v82, v84, v84
	v_add_f32_e32 v82, v83, v82
	v_add_f32_e32 v82, v82, v104
	v_mov_b32_e32 v83, v82
	s_nop 1
	v_permlane16_swap_b32_e32 v82, v83
	v_add_f32_e32 v82, v82, v83
	v_mov_b32_e32 v83, v82
	s_nop 1
	v_permlane32_swap_b32_e32 v82, v83
	v_cvt_pk_bf16_f32 v89, v84, v85
	global_store_dwordx4 v[102:103], v[86:89], off offset:256
	s_and_saveexec_b64 s[12:13], s[38:39]
	s_cbranch_execz .LBB0_995
	v_add_f32_e32 v84, v82, v83
	s_lshl_b32 s2, s57, 2
	v_lshlrev_b64 v[82:83], 6, v[100:101]
	s_ashr_i32 s3, s2, 31
	v_lshl_add_u64 v[82:83], s[8:9], 0, v[82:83]
	v_lshl_add_u64 v[82:83], s[2:3], 2, v[82:83]
	s_lshl_b32 s0, s51, 2
	v_lshl_add_u64 v[82:83], v[82:83], 0, s[0:1]
	global_store_dword v[82:83], v84, off
.LBB0_995:
	s_or_b64 exec, exec, s[12:13]
	v_bitop3_b32 v88, v142, s96, 48 bitop3:0xc8
	v_lshl_add_u64 v[82:83], v[98:99], 0, s[70:71]
	v_lshl_add_u32 v88, v88, 2, s15
	v_or_b32_e32 v84, 48, v142
	ds_read_b32 v88, v88
	v_ashrrev_i32_e32 v85, 31, v84
	v_lshlrev_b64 v[86:87], 10, v[84:85]
	v_lshl_add_u64 v[86:87], v[86:87], 0, v[140:141]
	v_lshlrev_b64 v[86:87], 1, v[86:87]
	s_waitcnt lgkmcnt(0)
	v_mul_f32_e32 v90, 0xbfb8aa3b, v88
	v_lshl_add_u64 v[88:89], s[6:7], 0, v[86:87]
	global_load_dwordx4 v[92:95], v[82:83], off
	v_mul_f32_e32 v78, v78, v90
	v_mul_f32_e32 v79, v79, v90
	v_mul_f32_e32 v80, v80, v90
	v_mul_f32_e32 v81, v81, v90
	v_exp_f32_e32 v78, v78
	v_exp_f32_e32 v79, v79
	v_exp_f32_e32 v80, v80
	v_exp_f32_e32 v81, v81
	v_mul_f32_e32 v74, v74, v90
	v_mul_f32_e32 v75, v75, v90
	v_add_f32_e32 v78, 1.0, v78
	v_add_f32_e32 v79, 1.0, v79
	v_add_f32_e32 v80, 1.0, v80
	v_add_f32_e32 v81, 1.0, v81
	v_exp_f32_e32 v74, v74
	v_exp_f32_e32 v75, v75
	v_mul_f32_e32 v76, v76, v90
	v_mul_f32_e32 v77, v77, v90
	v_rcp_f32_e32 v78, v78
	v_rcp_f32_e32 v79, v79
	v_rcp_f32_e32 v80, v80
	v_rcp_f32_e32 v81, v81
	v_exp_f32_e32 v76, v76
	v_exp_f32_e32 v77, v77
	v_add_f32_e32 v74, 1.0, v74
	v_add_f32_e32 v75, 1.0, v75
	v_rcp_f32_e32 v74, v74
	v_rcp_f32_e32 v75, v75
	v_add_f32_e32 v76, 1.0, v76
	v_add_f32_e32 v77, 1.0, v77
	v_rcp_f32_e32 v76, v76
	v_rcp_f32_e32 v77, v77
	v_lshl_add_u64 v[86:87], s[74:75], 0, v[86:87]
	v_mul_f32_e32 v70, v70, v90
	v_mul_f32_e32 v71, v71, v90
	v_mul_f32_e32 v72, v72, v90
	v_mul_f32_e32 v73, v73, v90
	v_exp_f32_e32 v70, v70
	v_exp_f32_e32 v71, v71
	v_exp_f32_e32 v72, v72
	v_exp_f32_e32 v73, v73
	v_add_f32_e32 v70, 1.0, v70
	v_add_f32_e32 v71, 1.0, v71
	v_add_f32_e32 v72, 1.0, v72
	v_add_f32_e32 v73, 1.0, v73
	v_mul_f32_e32 v66, v66, v90
	v_mul_f32_e32 v67, v67, v90
	v_rcp_f32_e32 v70, v70
	v_rcp_f32_e32 v71, v71
	v_rcp_f32_e32 v72, v72
	v_rcp_f32_e32 v73, v73
	v_exp_f32_e32 v66, v66
	v_exp_f32_e32 v67, v67
	v_mul_f32_e32 v68, v68, v90
	v_mul_f32_e32 v69, v69, v90
	v_exp_f32_e32 v68, v68
	v_exp_f32_e32 v69, v69
	v_add_f32_e32 v66, 1.0, v66
	v_add_f32_e32 v67, 1.0, v67
	v_rcp_f32_e32 v66, v66
	v_rcp_f32_e32 v67, v67
	v_add_f32_e32 v68, 1.0, v68
	v_add_f32_e32 v69, 1.0, v69
	v_rcp_f32_e32 v68, v68
	v_rcp_f32_e32 v69, v69
	s_waitcnt vmcnt(0)
	v_mov_b32_e32 v96, v214
	v_mov_b32_e32 v97, v215
	v_mov_b32_e32 v98, v216
	v_mov_b32_e32 v99, v217
	v_lshlrev_b32_e32 v102, 16, v92
	s_waitcnt vmcnt(0)
	v_lshlrev_b32_e32 v100, 16, v96
	v_and_b32_e32 v101, 0xffff0000, v96
	v_lshlrev_b32_e32 v96, 16, v97
	v_and_b32_e32 v97, 0xffff0000, v97
	v_and_b32_e32 v103, 0xffff0000, v92
	v_lshlrev_b32_e32 v92, 16, v93
	v_and_b32_e32 v93, 0xffff0000, v93
	v_pk_fma_f32 v[80:81], v[80:81], v[92:93], v[96:97]
	v_pk_fma_f32 v[92:93], v[78:79], v[102:103], v[100:101]
	v_lshlrev_b32_e32 v96, 16, v94
	v_cvt_pk_bf16_f32 v78, v92, v93
	v_cvt_pk_bf16_f32 v79, v80, v81
	v_mul_f32_e32 v91, v93, v93
	v_mul_f32_e32 v81, v81, v81
	v_fmac_f32_e32 v91, v92, v92
	v_fmac_f32_e32 v81, v80, v80
	v_add_f32_e32 v91, v91, v81
	v_lshlrev_b32_e32 v80, 16, v98
	v_and_b32_e32 v81, 0xffff0000, v98
	v_and_b32_e32 v97, 0xffff0000, v94
	v_lshlrev_b32_e32 v92, 16, v99
	v_and_b32_e32 v93, 0xffff0000, v99
	v_lshlrev_b32_e32 v94, 16, v95
	v_and_b32_e32 v95, 0xffff0000, v95
	v_pk_fma_f32 v[74:75], v[74:75], v[96:97], v[80:81]
	v_pk_fma_f32 v[76:77], v[76:77], v[94:95], v[92:93]
	v_cvt_pk_bf16_f32 v80, v74, v75
	v_mul_f32_e32 v75, v75, v75
	v_fmac_f32_e32 v75, v74, v74
	v_mul_f32_e32 v74, v77, v77
	v_fmac_f32_e32 v74, v76, v76
	v_cvt_pk_bf16_f32 v81, v76, v77
	v_add_f32_e32 v74, v75, v74
	global_store_dwordx4 v[86:87], v[78:81], off
	v_add_f32_e32 v91, v91, v74
	global_load_dwordx4 v[74:77], v[82:83], off offset:16
	s_waitcnt vmcnt(1)
	v_mov_b32_e32 v78, v218
	v_mov_b32_e32 v79, v219
	v_mov_b32_e32 v80, v220
	v_mov_b32_e32 v81, v221
	v_lshlrev_b32_e32 v88, 16, v78
	v_and_b32_e32 v89, 0xffff0000, v78
	v_lshlrev_b32_e32 v78, 16, v79
	v_and_b32_e32 v79, 0xffff0000, v79
	s_waitcnt vmcnt(0)
	v_lshlrev_b32_e32 v92, 16, v74
	v_and_b32_e32 v93, 0xffff0000, v74
	v_lshlrev_b32_e32 v74, 16, v75
	v_and_b32_e32 v75, 0xffff0000, v75
	v_pk_fma_f32 v[72:73], v[72:73], v[74:75], v[78:79]
	v_pk_fma_f32 v[74:75], v[70:71], v[92:93], v[88:89]
	v_lshlrev_b32_e32 v78, 16, v76
	v_cvt_pk_bf16_f32 v70, v74, v75
	v_cvt_pk_bf16_f32 v71, v72, v73
	v_mul_f32_e32 v75, v75, v75
	v_mul_f32_e32 v73, v73, v73
	v_fmac_f32_e32 v75, v74, v74
	v_fmac_f32_e32 v73, v72, v72
	v_add_f32_e32 v72, v75, v73
	v_add_f32_e32 v88, v91, v72
	v_lshlrev_b32_e32 v72, 16, v80
	v_and_b32_e32 v73, 0xffff0000, v80
	v_and_b32_e32 v79, 0xffff0000, v76
	v_lshlrev_b32_e32 v74, 16, v81
	v_and_b32_e32 v75, 0xffff0000, v81
	v_lshlrev_b32_e32 v76, 16, v77
	v_and_b32_e32 v77, 0xffff0000, v77
	v_pk_fma_f32 v[66:67], v[66:67], v[78:79], v[72:73]
	v_pk_fma_f32 v[68:69], v[68:69], v[76:77], v[74:75]
	v_cvt_pk_bf16_f32 v72, v66, v67
	v_mul_f32_e32 v67, v67, v67
	v_fmac_f32_e32 v67, v66, v66
	v_mul_f32_e32 v66, v69, v69
	v_fmac_f32_e32 v66, v68, v68
	v_add_f32_e32 v66, v67, v66
	v_add_f32_e32 v66, v66, v88
	v_mov_b32_e32 v67, v66
	s_nop 1
	v_permlane16_swap_b32_e32 v66, v67
	v_add_f32_e32 v66, v66, v67
	v_mov_b32_e32 v67, v66
	s_nop 1
	v_permlane32_swap_b32_e32 v66, v67
	v_cvt_pk_bf16_f32 v73, v68, v69
	global_store_dwordx4 v[86:87], v[70:73], off offset:256
	s_and_saveexec_b64 s[12:13], s[38:39]
	s_cbranch_execz .LBB0_997
	v_add_f32_e32 v68, v66, v67
	s_lshl_b32 s2, s57, 2
	v_lshlrev_b64 v[66:67], 6, v[84:85]
	s_ashr_i32 s3, s2, 31
	v_lshl_add_u64 v[66:67], s[8:9], 0, v[66:67]
	v_lshl_add_u64 v[66:67], s[2:3], 2, v[66:67]
	s_lshl_b32 s0, s51, 2
	v_lshl_add_u64 v[66:67], v[66:67], 0, s[0:1]
	global_store_dword v[66:67], v68, off
.LBB0_997:
	s_or_b64 exec, exec, s[12:13]
	v_add_u32_e32 v68, 0x80, v142
	v_lshl_add_u64 v[66:67], v[82:83], 0, s[70:71]
	v_and_b32_e32 v72, 0xcf, v68
	v_lshl_add_u32 v72, v72, 2, s15
	ds_read_b32 v72, v72
	v_ashrrev_i32_e32 v69, 31, v68
	v_lshlrev_b64 v[70:71], 10, v[68:69]
	v_lshl_add_u64 v[70:71], v[70:71], 0, v[140:141]
	v_lshlrev_b64 v[70:71], 1, v[70:71]
	s_waitcnt lgkmcnt(0)
	v_mul_f32_e32 v74, 0xbfb8aa3b, v72
	v_lshl_add_u64 v[72:73], s[6:7], 0, v[70:71]
	global_load_dwordx4 v[80:83], v[66:67], off
	v_mul_f32_e32 v62, v62, v74
	v_mul_f32_e32 v63, v63, v74
	v_mul_f32_e32 v64, v64, v74
	v_mul_f32_e32 v65, v65, v74
	v_exp_f32_e32 v62, v62
	v_exp_f32_e32 v63, v63
	v_exp_f32_e32 v64, v64
	v_exp_f32_e32 v65, v65
	v_mul_f32_e32 v58, v58, v74
	v_mul_f32_e32 v59, v59, v74
	v_add_f32_e32 v62, 1.0, v62
	v_add_f32_e32 v63, 1.0, v63
	v_add_f32_e32 v64, 1.0, v64
	v_add_f32_e32 v65, 1.0, v65
	v_exp_f32_e32 v58, v58
	v_exp_f32_e32 v59, v59
	v_mul_f32_e32 v60, v60, v74
	v_mul_f32_e32 v61, v61, v74
	v_rcp_f32_e32 v62, v62
	v_rcp_f32_e32 v63, v63
	v_rcp_f32_e32 v64, v64
	v_rcp_f32_e32 v65, v65
	v_exp_f32_e32 v60, v60
	v_exp_f32_e32 v61, v61
	v_add_f32_e32 v58, 1.0, v58
	v_add_f32_e32 v59, 1.0, v59
	v_rcp_f32_e32 v58, v58
	v_rcp_f32_e32 v59, v59
	v_add_f32_e32 v60, 1.0, v60
	v_add_f32_e32 v61, 1.0, v61
	v_rcp_f32_e32 v60, v60
	v_rcp_f32_e32 v61, v61
	v_lshl_add_u64 v[70:71], s[74:75], 0, v[70:71]
	v_mul_f32_e32 v54, v54, v74
	v_mul_f32_e32 v55, v55, v74
	v_mul_f32_e32 v56, v56, v74
	v_mul_f32_e32 v57, v57, v74
	v_exp_f32_e32 v54, v54
	v_exp_f32_e32 v55, v55
	v_exp_f32_e32 v56, v56
	v_exp_f32_e32 v57, v57
	v_add_f32_e32 v54, 1.0, v54
	v_add_f32_e32 v55, 1.0, v55
	v_add_f32_e32 v56, 1.0, v56
	v_add_f32_e32 v57, 1.0, v57
	v_mul_f32_e32 v50, v50, v74
	v_mul_f32_e32 v51, v51, v74
	v_rcp_f32_e32 v54, v54
	v_rcp_f32_e32 v55, v55
	v_rcp_f32_e32 v56, v56
	v_rcp_f32_e32 v57, v57
	v_exp_f32_e32 v50, v50
	v_exp_f32_e32 v51, v51
	v_mul_f32_e32 v52, v52, v74
	v_mul_f32_e32 v53, v53, v74
	v_exp_f32_e32 v52, v52
	v_exp_f32_e32 v53, v53
	v_add_f32_e32 v50, 1.0, v50
	v_add_f32_e32 v51, 1.0, v51
	v_rcp_f32_e32 v50, v50
	v_rcp_f32_e32 v51, v51
	v_add_f32_e32 v52, 1.0, v52
	v_add_f32_e32 v53, 1.0, v53
	v_rcp_f32_e32 v52, v52
	v_rcp_f32_e32 v53, v53
	s_waitcnt vmcnt(1)
	v_mov_b32_e32 v76, v222
	v_mov_b32_e32 v77, v223
	v_mov_b32_e32 v78, v224
	v_mov_b32_e32 v79, v225
	v_lshlrev_b32_e32 v84, 16, v76
	v_and_b32_e32 v85, 0xffff0000, v76
	v_lshlrev_b32_e32 v76, 16, v77
	v_and_b32_e32 v77, 0xffff0000, v77
	s_waitcnt vmcnt(0)
	v_lshlrev_b32_e32 v86, 16, v80
	v_and_b32_e32 v87, 0xffff0000, v80
	v_lshlrev_b32_e32 v80, 16, v81
	v_and_b32_e32 v81, 0xffff0000, v81
	v_pk_fma_f32 v[64:65], v[64:65], v[80:81], v[76:77]
	v_pk_fma_f32 v[76:77], v[62:63], v[86:87], v[84:85]
	v_lshlrev_b32_e32 v80, 16, v83
	v_cvt_pk_bf16_f32 v62, v76, v77
	v_cvt_pk_bf16_f32 v63, v64, v65
	v_mul_f32_e32 v75, v77, v77
	v_mul_f32_e32 v65, v65, v65
	v_fmac_f32_e32 v75, v76, v76
	v_fmac_f32_e32 v65, v64, v64
	v_add_f32_e32 v75, v75, v65
	v_lshlrev_b32_e32 v64, 16, v78
	v_and_b32_e32 v65, 0xffff0000, v78
	v_lshlrev_b32_e32 v76, 16, v79
	v_and_b32_e32 v77, 0xffff0000, v79
	v_lshlrev_b32_e32 v78, 16, v82
	v_and_b32_e32 v79, 0xffff0000, v82
	v_and_b32_e32 v81, 0xffff0000, v83
	v_pk_fma_f32 v[58:59], v[58:59], v[78:79], v[64:65]
	v_pk_fma_f32 v[60:61], v[60:61], v[80:81], v[76:77]
	v_cvt_pk_bf16_f32 v64, v58, v59
	v_mul_f32_e32 v59, v59, v59
	v_fmac_f32_e32 v59, v58, v58
	v_mul_f32_e32 v58, v61, v61
	v_fmac_f32_e32 v58, v60, v60
	v_cvt_pk_bf16_f32 v65, v60, v61
	v_add_f32_e32 v58, v59, v58
	global_store_dwordx4 v[70:71], v[62:65], off
	v_add_f32_e32 v75, v75, v58
	global_load_dwordx4 v[58:61], v[66:67], off offset:16
	s_waitcnt vmcnt(1)
	v_mov_b32_e32 v62, v226
	v_mov_b32_e32 v63, v227
	v_mov_b32_e32 v64, v228
	v_mov_b32_e32 v65, v229
	v_lshlrev_b32_e32 v72, 16, v62
	v_and_b32_e32 v73, 0xffff0000, v62
	v_lshlrev_b32_e32 v62, 16, v63
	v_and_b32_e32 v63, 0xffff0000, v63
	s_waitcnt vmcnt(0)
	v_lshlrev_b32_e32 v76, 16, v58
	v_and_b32_e32 v77, 0xffff0000, v58
	v_lshlrev_b32_e32 v58, 16, v59
	v_and_b32_e32 v59, 0xffff0000, v59
	v_pk_fma_f32 v[56:57], v[56:57], v[58:59], v[62:63]
	v_pk_fma_f32 v[58:59], v[54:55], v[76:77], v[72:73]
	v_lshlrev_b32_e32 v62, 16, v60
	v_cvt_pk_bf16_f32 v54, v58, v59
	v_cvt_pk_bf16_f32 v55, v56, v57
	v_mul_f32_e32 v59, v59, v59
	v_mul_f32_e32 v57, v57, v57
	v_fmac_f32_e32 v59, v58, v58
	v_fmac_f32_e32 v57, v56, v56
	v_add_f32_e32 v56, v59, v57
	v_add_f32_e32 v72, v75, v56
	v_lshlrev_b32_e32 v56, 16, v64
	v_and_b32_e32 v57, 0xffff0000, v64
	v_and_b32_e32 v63, 0xffff0000, v60
	v_lshlrev_b32_e32 v58, 16, v65
	v_and_b32_e32 v59, 0xffff0000, v65
	v_lshlrev_b32_e32 v60, 16, v61
	v_and_b32_e32 v61, 0xffff0000, v61
	v_pk_fma_f32 v[50:51], v[50:51], v[62:63], v[56:57]
	v_pk_fma_f32 v[52:53], v[52:53], v[60:61], v[58:59]
	v_cvt_pk_bf16_f32 v56, v50, v51
	v_mul_f32_e32 v51, v51, v51
	v_fmac_f32_e32 v51, v50, v50
	v_mul_f32_e32 v50, v53, v53
	v_fmac_f32_e32 v50, v52, v52
	v_add_f32_e32 v50, v51, v50
	v_add_f32_e32 v50, v50, v72
	v_mov_b32_e32 v51, v50
	s_nop 1
	v_permlane16_swap_b32_e32 v50, v51
	v_add_f32_e32 v50, v50, v51
	v_mov_b32_e32 v51, v50
	s_nop 1
	v_permlane32_swap_b32_e32 v50, v51
	v_cvt_pk_bf16_f32 v57, v52, v53
	global_store_dwordx4 v[70:71], v[54:57], off offset:256
	s_and_saveexec_b64 s[12:13], s[38:39]
	s_cbranch_execz .LBB0_999
	v_add_f32_e32 v52, v50, v51
	s_lshl_b32 s2, s57, 2
	v_lshlrev_b64 v[50:51], 6, v[68:69]
	s_ashr_i32 s3, s2, 31
	v_lshl_add_u64 v[50:51], s[8:9], 0, v[50:51]
	v_lshl_add_u64 v[50:51], s[2:3], 2, v[50:51]
	s_lshl_b32 s0, s51, 2
	v_lshl_add_u64 v[50:51], v[50:51], 0, s[0:1]
	global_store_dword v[50:51], v52, off
.LBB0_999:
	s_or_b64 exec, exec, s[12:13]
	v_add_u32_e32 v52, 0x90, v142
	v_and_b32_e32 v56, 0xdf, v52
	v_lshl_add_u64 v[50:51], v[66:67], 0, s[70:71]
	v_lshl_add_u32 v56, v56, 2, s15
	ds_read_b32 v56, v56
	v_ashrrev_i32_e32 v53, 31, v52
	v_lshlrev_b64 v[54:55], 10, v[52:53]
	v_lshl_add_u64 v[54:55], v[54:55], 0, v[140:141]
	v_lshlrev_b64 v[54:55], 1, v[54:55]
	s_waitcnt lgkmcnt(0)
	v_mul_f32_e32 v58, 0xbfb8aa3b, v56
	v_lshl_add_u64 v[56:57], s[6:7], 0, v[54:55]
	global_load_dwordx4 v[60:63], v[50:51], off
	v_mul_f32_e32 v46, v46, v58
	v_mul_f32_e32 v47, v47, v58
	v_mul_f32_e32 v48, v48, v58
	v_mul_f32_e32 v49, v49, v58
	v_exp_f32_e32 v46, v46
	v_exp_f32_e32 v47, v47
	v_exp_f32_e32 v48, v48
	v_exp_f32_e32 v49, v49
	v_mul_f32_e32 v42, v42, v58
	v_mul_f32_e32 v43, v43, v58
	v_add_f32_e32 v46, 1.0, v46
	v_add_f32_e32 v47, 1.0, v47
	v_add_f32_e32 v48, 1.0, v48
	v_add_f32_e32 v49, 1.0, v49
	v_exp_f32_e32 v42, v42
	v_exp_f32_e32 v43, v43
	v_mul_f32_e32 v44, v44, v58
	v_mul_f32_e32 v45, v45, v58
	v_rcp_f32_e32 v46, v46
	v_rcp_f32_e32 v47, v47
	v_rcp_f32_e32 v48, v48
	v_rcp_f32_e32 v49, v49
	v_exp_f32_e32 v44, v44
	v_exp_f32_e32 v45, v45
	v_add_f32_e32 v42, 1.0, v42
	v_add_f32_e32 v43, 1.0, v43
	v_rcp_f32_e32 v42, v42
	v_rcp_f32_e32 v43, v43
	v_add_f32_e32 v44, 1.0, v44
	v_add_f32_e32 v45, 1.0, v45
	v_rcp_f32_e32 v44, v44
	v_rcp_f32_e32 v45, v45
	v_lshl_add_u64 v[54:55], s[74:75], 0, v[54:55]
	v_mul_f32_e32 v38, v38, v58
	v_mul_f32_e32 v39, v39, v58
	v_mul_f32_e32 v40, v40, v58
	v_mul_f32_e32 v41, v41, v58
	v_exp_f32_e32 v38, v38
	v_exp_f32_e32 v39, v39
	v_exp_f32_e32 v40, v40
	v_exp_f32_e32 v41, v41
	v_add_f32_e32 v38, 1.0, v38
	v_add_f32_e32 v39, 1.0, v39
	v_add_f32_e32 v40, 1.0, v40
	v_add_f32_e32 v41, 1.0, v41
	v_mul_f32_e32 v34, v34, v58
	v_mul_f32_e32 v35, v35, v58
	v_rcp_f32_e32 v38, v38
	v_rcp_f32_e32 v39, v39
	v_rcp_f32_e32 v40, v40
	v_rcp_f32_e32 v41, v41
	v_exp_f32_e32 v34, v34
	v_exp_f32_e32 v35, v35
	v_mul_f32_e32 v36, v36, v58
	v_mul_f32_e32 v37, v37, v58
	v_exp_f32_e32 v36, v36
	v_exp_f32_e32 v37, v37
	v_add_f32_e32 v34, 1.0, v34
	v_add_f32_e32 v35, 1.0, v35
	v_rcp_f32_e32 v34, v34
	v_rcp_f32_e32 v35, v35
	v_add_f32_e32 v36, 1.0, v36
	v_add_f32_e32 v37, 1.0, v37
	v_rcp_f32_e32 v36, v36
	v_rcp_f32_e32 v37, v37
	s_waitcnt vmcnt(0)
	v_mov_b32_e32 v64, v230
	v_mov_b32_e32 v65, v231
	v_mov_b32_e32 v66, v232
	v_mov_b32_e32 v67, v233
	v_lshlrev_b32_e32 v70, 16, v60
	s_waitcnt vmcnt(0)
	v_lshlrev_b32_e32 v68, 16, v64
	v_and_b32_e32 v69, 0xffff0000, v64
	v_lshlrev_b32_e32 v64, 16, v65
	v_and_b32_e32 v65, 0xffff0000, v65
	v_and_b32_e32 v71, 0xffff0000, v60
	v_lshlrev_b32_e32 v60, 16, v61
	v_and_b32_e32 v61, 0xffff0000, v61
	v_pk_fma_f32 v[48:49], v[48:49], v[60:61], v[64:65]
	v_pk_fma_f32 v[60:61], v[46:47], v[70:71], v[68:69]
	v_lshlrev_b32_e32 v64, 16, v62
	v_cvt_pk_bf16_f32 v46, v60, v61
	v_cvt_pk_bf16_f32 v47, v48, v49
	v_mul_f32_e32 v59, v61, v61
	v_mul_f32_e32 v49, v49, v49
	v_fmac_f32_e32 v59, v60, v60
	v_fmac_f32_e32 v49, v48, v48
	v_add_f32_e32 v59, v59, v49
	v_lshlrev_b32_e32 v48, 16, v66
	v_and_b32_e32 v49, 0xffff0000, v66
	v_and_b32_e32 v65, 0xffff0000, v62
	v_lshlrev_b32_e32 v60, 16, v67
	v_and_b32_e32 v61, 0xffff0000, v67
	v_lshlrev_b32_e32 v62, 16, v63
	v_and_b32_e32 v63, 0xffff0000, v63
	v_pk_fma_f32 v[42:43], v[42:43], v[64:65], v[48:49]
	v_pk_fma_f32 v[44:45], v[44:45], v[62:63], v[60:61]
	v_cvt_pk_bf16_f32 v48, v42, v43
	v_mul_f32_e32 v43, v43, v43
	v_fmac_f32_e32 v43, v42, v42
	v_mul_f32_e32 v42, v45, v45
	v_fmac_f32_e32 v42, v44, v44
	v_cvt_pk_bf16_f32 v49, v44, v45
	v_add_f32_e32 v42, v43, v42
	global_store_dwordx4 v[54:55], v[46:49], off
	v_add_f32_e32 v59, v59, v42
	global_load_dwordx4 v[42:45], v[50:51], off offset:16
	s_waitcnt vmcnt(1)
	v_mov_b32_e32 v46, v234
	v_mov_b32_e32 v47, v235
	v_mov_b32_e32 v48, v236
	v_mov_b32_e32 v49, v237
	v_lshlrev_b32_e32 v56, 16, v46
	v_and_b32_e32 v57, 0xffff0000, v46
	v_lshlrev_b32_e32 v46, 16, v47
	v_and_b32_e32 v47, 0xffff0000, v47
	s_waitcnt vmcnt(0)
	v_lshlrev_b32_e32 v60, 16, v42
	v_and_b32_e32 v61, 0xffff0000, v42
	v_lshlrev_b32_e32 v42, 16, v43
	v_and_b32_e32 v43, 0xffff0000, v43
	v_pk_fma_f32 v[40:41], v[40:41], v[42:43], v[46:47]
	v_pk_fma_f32 v[42:43], v[38:39], v[60:61], v[56:57]
	v_lshlrev_b32_e32 v46, 16, v44
	v_cvt_pk_bf16_f32 v38, v42, v43
	v_cvt_pk_bf16_f32 v39, v40, v41
	v_mul_f32_e32 v43, v43, v43
	v_mul_f32_e32 v41, v41, v41
	v_fmac_f32_e32 v43, v42, v42
	v_fmac_f32_e32 v41, v40, v40
	v_add_f32_e32 v40, v43, v41
	v_add_f32_e32 v56, v59, v40
	v_lshlrev_b32_e32 v40, 16, v48
	v_and_b32_e32 v41, 0xffff0000, v48
	v_and_b32_e32 v47, 0xffff0000, v44
	v_lshlrev_b32_e32 v42, 16, v49
	v_and_b32_e32 v43, 0xffff0000, v49
	v_lshlrev_b32_e32 v44, 16, v45
	v_and_b32_e32 v45, 0xffff0000, v45
	v_pk_fma_f32 v[34:35], v[34:35], v[46:47], v[40:41]
	v_pk_fma_f32 v[36:37], v[36:37], v[44:45], v[42:43]
	v_cvt_pk_bf16_f32 v40, v34, v35
	v_mul_f32_e32 v35, v35, v35
	v_fmac_f32_e32 v35, v34, v34
	v_mul_f32_e32 v34, v37, v37
	v_fmac_f32_e32 v34, v36, v36
	v_add_f32_e32 v34, v35, v34
	v_add_f32_e32 v34, v34, v56
	v_mov_b32_e32 v35, v34
	s_nop 1
	v_permlane16_swap_b32_e32 v34, v35
	v_add_f32_e32 v34, v34, v35
	v_mov_b32_e32 v35, v34
	s_nop 1
	v_permlane32_swap_b32_e32 v34, v35
	v_cvt_pk_bf16_f32 v41, v36, v37
	global_store_dwordx4 v[54:55], v[38:41], off offset:256
	s_and_saveexec_b64 s[12:13], s[38:39]
	s_cbranch_execz .LBB0_1001
	v_add_f32_e32 v36, v34, v35
	s_lshl_b32 s2, s57, 2
	v_lshlrev_b64 v[34:35], 6, v[52:53]
	s_ashr_i32 s3, s2, 31
	v_lshl_add_u64 v[34:35], s[8:9], 0, v[34:35]
	v_lshl_add_u64 v[34:35], s[2:3], 2, v[34:35]
	s_lshl_b32 s0, s51, 2
	v_lshl_add_u64 v[34:35], v[34:35], 0, s[0:1]
	global_store_dword v[34:35], v36, off
.LBB0_1001:
	s_or_b64 exec, exec, s[12:13]
	v_add_u32_e32 v36, 0xa0, v142
	v_lshl_add_u64 v[34:35], v[50:51], 0, s[70:71]
	v_and_b32_e32 v40, 0xef, v36
	v_lshl_add_u32 v40, v40, 2, s15
	ds_read_b32 v40, v40
	v_ashrrev_i32_e32 v37, 31, v36
	v_lshlrev_b64 v[38:39], 10, v[36:37]
	v_lshl_add_u64 v[38:39], v[38:39], 0, v[140:141]
	v_lshlrev_b64 v[38:39], 1, v[38:39]
	s_waitcnt lgkmcnt(0)
	v_mul_f32_e32 v42, 0xbfb8aa3b, v40
	v_lshl_add_u64 v[40:41], s[6:7], 0, v[38:39]
	global_load_dwordx4 v[48:51], v[34:35], off
	v_mul_f32_e32 v30, v30, v42
	v_mul_f32_e32 v31, v31, v42
	v_mul_f32_e32 v32, v32, v42
	v_mul_f32_e32 v33, v33, v42
	v_exp_f32_e32 v30, v30
	v_exp_f32_e32 v31, v31
	v_exp_f32_e32 v32, v32
	v_exp_f32_e32 v33, v33
	v_mul_f32_e32 v26, v26, v42
	v_mul_f32_e32 v27, v27, v42
	v_add_f32_e32 v30, 1.0, v30
	v_add_f32_e32 v31, 1.0, v31
	v_add_f32_e32 v32, 1.0, v32
	v_add_f32_e32 v33, 1.0, v33
	v_exp_f32_e32 v26, v26
	v_exp_f32_e32 v27, v27
	v_mul_f32_e32 v28, v28, v42
	v_mul_f32_e32 v29, v29, v42
	v_rcp_f32_e32 v30, v30
	v_rcp_f32_e32 v31, v31
	v_rcp_f32_e32 v32, v32
	v_rcp_f32_e32 v33, v33
	v_exp_f32_e32 v28, v28
	v_exp_f32_e32 v29, v29
	v_add_f32_e32 v26, 1.0, v26
	v_add_f32_e32 v27, 1.0, v27
	v_rcp_f32_e32 v26, v26
	v_rcp_f32_e32 v27, v27
	v_add_f32_e32 v28, 1.0, v28
	v_add_f32_e32 v29, 1.0, v29
	v_rcp_f32_e32 v28, v28
	v_rcp_f32_e32 v29, v29
	v_lshl_add_u64 v[38:39], s[74:75], 0, v[38:39]
	v_mul_f32_e32 v22, v22, v42
	v_mul_f32_e32 v23, v23, v42
	v_mul_f32_e32 v24, v24, v42
	v_mul_f32_e32 v25, v25, v42
	v_exp_f32_e32 v22, v22
	v_exp_f32_e32 v23, v23
	v_exp_f32_e32 v24, v24
	v_exp_f32_e32 v25, v25
	v_add_f32_e32 v22, 1.0, v22
	v_add_f32_e32 v23, 1.0, v23
	v_add_f32_e32 v24, 1.0, v24
	v_add_f32_e32 v25, 1.0, v25
	v_mul_f32_e32 v18, v18, v42
	v_mul_f32_e32 v19, v19, v42
	v_rcp_f32_e32 v22, v22
	v_rcp_f32_e32 v23, v23
	v_rcp_f32_e32 v24, v24
	v_rcp_f32_e32 v25, v25
	v_exp_f32_e32 v18, v18
	v_exp_f32_e32 v19, v19
	v_mul_f32_e32 v20, v20, v42
	v_mul_f32_e32 v21, v21, v42
	v_exp_f32_e32 v20, v20
	v_exp_f32_e32 v21, v21
	v_add_f32_e32 v18, 1.0, v18
	v_add_f32_e32 v19, 1.0, v19
	v_rcp_f32_e32 v18, v18
	v_rcp_f32_e32 v19, v19
	v_add_f32_e32 v20, 1.0, v20
	v_add_f32_e32 v21, 1.0, v21
	v_rcp_f32_e32 v20, v20
	v_rcp_f32_e32 v21, v21
	s_waitcnt vmcnt(1)
	v_mov_b32_e32 v44, v238
	v_mov_b32_e32 v45, v239
	v_mov_b32_e32 v46, v240
	v_mov_b32_e32 v47, v241
	v_lshlrev_b32_e32 v52, 16, v44
	v_and_b32_e32 v53, 0xffff0000, v44
	v_lshlrev_b32_e32 v44, 16, v45
	v_and_b32_e32 v45, 0xffff0000, v45
	s_waitcnt vmcnt(0)
	v_lshlrev_b32_e32 v54, 16, v48
	v_and_b32_e32 v55, 0xffff0000, v48
	v_lshlrev_b32_e32 v48, 16, v49
	v_and_b32_e32 v49, 0xffff0000, v49
	v_pk_fma_f32 v[32:33], v[32:33], v[48:49], v[44:45]
	v_pk_fma_f32 v[44:45], v[30:31], v[54:55], v[52:53]
	v_lshlrev_b32_e32 v48, 16, v51
	v_cvt_pk_bf16_f32 v30, v44, v45
	v_cvt_pk_bf16_f32 v31, v32, v33
	v_mul_f32_e32 v43, v45, v45
	v_mul_f32_e32 v33, v33, v33
	v_fmac_f32_e32 v43, v44, v44
	v_fmac_f32_e32 v33, v32, v32
	v_add_f32_e32 v43, v43, v33
	v_lshlrev_b32_e32 v32, 16, v46
	v_and_b32_e32 v33, 0xffff0000, v46
	v_lshlrev_b32_e32 v44, 16, v47
	v_and_b32_e32 v45, 0xffff0000, v47
	v_lshlrev_b32_e32 v46, 16, v50
	v_and_b32_e32 v47, 0xffff0000, v50
	v_and_b32_e32 v49, 0xffff0000, v51
	v_pk_fma_f32 v[26:27], v[26:27], v[46:47], v[32:33]
	v_pk_fma_f32 v[28:29], v[28:29], v[48:49], v[44:45]
	v_cvt_pk_bf16_f32 v32, v26, v27
	v_mul_f32_e32 v27, v27, v27
	v_fmac_f32_e32 v27, v26, v26
	v_mul_f32_e32 v26, v29, v29
	v_fmac_f32_e32 v26, v28, v28
	v_cvt_pk_bf16_f32 v33, v28, v29
	v_add_f32_e32 v26, v27, v26
	global_store_dwordx4 v[38:39], v[30:33], off
	v_add_f32_e32 v43, v43, v26
	global_load_dwordx4 v[26:29], v[34:35], off offset:16
	s_waitcnt vmcnt(1)
	v_mov_b32_e32 v30, v242
	v_mov_b32_e32 v31, v243
	v_mov_b32_e32 v32, v244
	v_mov_b32_e32 v33, v245
	v_lshlrev_b32_e32 v40, 16, v30
	v_and_b32_e32 v41, 0xffff0000, v30
	v_lshlrev_b32_e32 v30, 16, v31
	v_and_b32_e32 v31, 0xffff0000, v31
	s_waitcnt vmcnt(0)
	v_lshlrev_b32_e32 v44, 16, v26
	v_and_b32_e32 v45, 0xffff0000, v26
	v_lshlrev_b32_e32 v26, 16, v27
	v_and_b32_e32 v27, 0xffff0000, v27
	v_pk_fma_f32 v[24:25], v[24:25], v[26:27], v[30:31]
	v_pk_fma_f32 v[26:27], v[22:23], v[44:45], v[40:41]
	v_lshlrev_b32_e32 v30, 16, v28
	v_cvt_pk_bf16_f32 v22, v26, v27
	v_cvt_pk_bf16_f32 v23, v24, v25
	v_mul_f32_e32 v27, v27, v27
	v_mul_f32_e32 v25, v25, v25
	v_fmac_f32_e32 v27, v26, v26
	v_fmac_f32_e32 v25, v24, v24
	v_add_f32_e32 v24, v27, v25
	v_add_f32_e32 v40, v43, v24
	v_lshlrev_b32_e32 v24, 16, v32
	v_and_b32_e32 v25, 0xffff0000, v32
	v_and_b32_e32 v31, 0xffff0000, v28
	v_lshlrev_b32_e32 v26, 16, v33
	v_and_b32_e32 v27, 0xffff0000, v33
	v_lshlrev_b32_e32 v28, 16, v29
	v_and_b32_e32 v29, 0xffff0000, v29
	v_pk_fma_f32 v[18:19], v[18:19], v[30:31], v[24:25]
	v_pk_fma_f32 v[20:21], v[20:21], v[28:29], v[26:27]
	v_cvt_pk_bf16_f32 v24, v18, v19
	v_mul_f32_e32 v19, v19, v19
	v_fmac_f32_e32 v19, v18, v18
	v_mul_f32_e32 v18, v21, v21
	v_fmac_f32_e32 v18, v20, v20
	v_add_f32_e32 v18, v19, v18
	v_add_f32_e32 v18, v18, v40
	v_mov_b32_e32 v19, v18
	s_nop 1
	v_permlane16_swap_b32_e32 v18, v19
	v_add_f32_e32 v18, v18, v19
	v_mov_b32_e32 v19, v18
	s_nop 1
	v_permlane32_swap_b32_e32 v18, v19
	v_cvt_pk_bf16_f32 v25, v20, v21
	global_store_dwordx4 v[38:39], v[22:25], off offset:256
	s_and_saveexec_b64 s[12:13], s[38:39]
	s_cbranch_execz .LBB0_1003
	v_add_f32_e32 v20, v18, v19
	s_lshl_b32 s2, s57, 2
	v_lshlrev_b64 v[18:19], 6, v[36:37]
	s_ashr_i32 s3, s2, 31
	v_lshl_add_u64 v[18:19], s[8:9], 0, v[18:19]
	v_lshl_add_u64 v[18:19], s[2:3], 2, v[18:19]
	s_lshl_b32 s0, s51, 2
	v_lshl_add_u64 v[18:19], v[18:19], 0, s[0:1]
	global_store_dword v[18:19], v20, off
.LBB0_1003:
	s_or_b64 exec, exec, s[12:13]
	v_add_u32_e32 v20, 0xb0, v142
	v_and_b32_e32 v24, 0xff, v20
	v_lshl_add_u64 v[18:19], v[34:35], 0, s[70:71]
	v_lshl_add_u32 v24, v24, 2, s15
	ds_read_b32 v24, v24
	v_ashrrev_i32_e32 v21, 31, v20
	v_lshlrev_b64 v[22:23], 10, v[20:21]
	v_lshl_add_u64 v[22:23], v[22:23], 0, v[140:141]
	v_lshlrev_b64 v[22:23], 1, v[22:23]
	s_waitcnt lgkmcnt(0)
	v_mul_f32_e32 v26, 0xbfb8aa3b, v24
	v_lshl_add_u64 v[24:25], s[6:7], 0, v[22:23]
	global_load_dwordx4 v[28:31], v[18:19], off
	v_mul_f32_e32 v14, v14, v26
	v_mul_f32_e32 v15, v15, v26
	v_mul_f32_e32 v16, v16, v26
	v_mul_f32_e32 v17, v17, v26
	v_exp_f32_e32 v14, v14
	v_exp_f32_e32 v15, v15
	v_exp_f32_e32 v16, v16
	v_exp_f32_e32 v17, v17
	v_mul_f32_e32 v10, v10, v26
	v_mul_f32_e32 v11, v11, v26
	v_add_f32_e32 v14, 1.0, v14
	v_add_f32_e32 v15, 1.0, v15
	v_add_f32_e32 v16, 1.0, v16
	v_add_f32_e32 v17, 1.0, v17
	v_exp_f32_e32 v10, v10
	v_exp_f32_e32 v11, v11
	v_mul_f32_e32 v12, v12, v26
	v_mul_f32_e32 v13, v13, v26
	v_rcp_f32_e32 v14, v14
	v_rcp_f32_e32 v15, v15
	v_rcp_f32_e32 v16, v16
	v_rcp_f32_e32 v17, v17
	v_exp_f32_e32 v12, v12
	v_exp_f32_e32 v13, v13
	v_add_f32_e32 v10, 1.0, v10
	v_add_f32_e32 v11, 1.0, v11
	v_rcp_f32_e32 v10, v10
	v_rcp_f32_e32 v11, v11
	v_add_f32_e32 v12, 1.0, v12
	v_add_f32_e32 v13, 1.0, v13
	v_rcp_f32_e32 v12, v12
	v_rcp_f32_e32 v13, v13
	v_lshl_add_u64 v[22:23], s[74:75], 0, v[22:23]
	v_mul_f32_e32 v6, v6, v26
	v_mul_f32_e32 v7, v7, v26
	v_mul_f32_e32 v8, v8, v26
	v_mul_f32_e32 v9, v9, v26
	v_exp_f32_e32 v6, v6
	v_exp_f32_e32 v7, v7
	v_exp_f32_e32 v8, v8
	v_exp_f32_e32 v9, v9
	v_add_f32_e32 v6, 1.0, v6
	v_add_f32_e32 v7, 1.0, v7
	v_add_f32_e32 v8, 1.0, v8
	v_add_f32_e32 v9, 1.0, v9
	v_mul_f32_e32 v2, v2, v26
	v_mul_f32_e32 v3, v3, v26
	v_rcp_f32_e32 v6, v6
	v_rcp_f32_e32 v7, v7
	v_rcp_f32_e32 v8, v8
	v_rcp_f32_e32 v9, v9
	v_exp_f32_e32 v2, v2
	v_exp_f32_e32 v3, v3
	v_mul_f32_e32 v4, v4, v26
	v_mul_f32_e32 v5, v5, v26
	v_exp_f32_e32 v4, v4
	v_exp_f32_e32 v5, v5
	v_add_f32_e32 v2, 1.0, v2
	v_add_f32_e32 v3, 1.0, v3
	v_rcp_f32_e32 v2, v2
	v_rcp_f32_e32 v3, v3
	v_add_f32_e32 v4, 1.0, v4
	v_add_f32_e32 v5, 1.0, v5
	v_rcp_f32_e32 v4, v4
	v_rcp_f32_e32 v5, v5
	s_waitcnt vmcnt(0)
	v_mov_b32_e32 v32, v246
	v_mov_b32_e32 v33, v247
	v_mov_b32_e32 v34, v248
	v_mov_b32_e32 v35, v249
	v_lshlrev_b32_e32 v38, 16, v28
	s_waitcnt vmcnt(0)
	v_lshlrev_b32_e32 v36, 16, v32
	v_and_b32_e32 v37, 0xffff0000, v32
	v_lshlrev_b32_e32 v32, 16, v33
	v_and_b32_e32 v33, 0xffff0000, v33
	v_and_b32_e32 v39, 0xffff0000, v28
	v_lshlrev_b32_e32 v28, 16, v29
	v_and_b32_e32 v29, 0xffff0000, v29
	v_pk_fma_f32 v[16:17], v[16:17], v[28:29], v[32:33]
	v_pk_fma_f32 v[28:29], v[14:15], v[38:39], v[36:37]
	v_lshlrev_b32_e32 v32, 16, v30
	v_cvt_pk_bf16_f32 v14, v28, v29
	v_cvt_pk_bf16_f32 v15, v16, v17
	v_mul_f32_e32 v27, v29, v29
	v_mul_f32_e32 v17, v17, v17
	v_fmac_f32_e32 v27, v28, v28
	v_fmac_f32_e32 v17, v16, v16
	v_add_f32_e32 v27, v27, v17
	v_lshlrev_b32_e32 v16, 16, v34
	v_and_b32_e32 v17, 0xffff0000, v34
	v_and_b32_e32 v33, 0xffff0000, v30
	v_lshlrev_b32_e32 v28, 16, v35
	v_and_b32_e32 v29, 0xffff0000, v35
	v_lshlrev_b32_e32 v30, 16, v31
	v_and_b32_e32 v31, 0xffff0000, v31
	v_pk_fma_f32 v[10:11], v[10:11], v[32:33], v[16:17]
	v_pk_fma_f32 v[12:13], v[12:13], v[30:31], v[28:29]
	v_cvt_pk_bf16_f32 v16, v10, v11
	v_mul_f32_e32 v11, v11, v11
	v_fmac_f32_e32 v11, v10, v10
	v_mul_f32_e32 v10, v13, v13
	v_fmac_f32_e32 v10, v12, v12
	v_cvt_pk_bf16_f32 v17, v12, v13
	v_add_f32_e32 v10, v11, v10
	global_store_dwordx4 v[22:23], v[14:17], off
	v_add_f32_e32 v27, v27, v10
	global_load_dwordx4 v[14:17], v[24:25], off offset:256
	global_load_dwordx4 v[10:13], v[18:19], off offset:16
	s_waitcnt vmcnt(1)
	v_lshlrev_b32_e32 v24, 16, v14
	v_and_b32_e32 v25, 0xffff0000, v14
	v_lshlrev_b32_e32 v14, 16, v15
	v_and_b32_e32 v15, 0xffff0000, v15
	s_waitcnt vmcnt(0)
	v_lshlrev_b32_e32 v28, 16, v10
	v_and_b32_e32 v29, 0xffff0000, v10
	v_lshlrev_b32_e32 v10, 16, v11
	v_and_b32_e32 v11, 0xffff0000, v11
	v_pk_fma_f32 v[8:9], v[8:9], v[10:11], v[14:15]
	v_pk_fma_f32 v[10:11], v[6:7], v[28:29], v[24:25]
	v_lshlrev_b32_e32 v14, 16, v12
	v_cvt_pk_bf16_f32 v6, v10, v11
	v_cvt_pk_bf16_f32 v7, v8, v9
	v_mul_f32_e32 v11, v11, v11
	v_mul_f32_e32 v9, v9, v9
	v_fmac_f32_e32 v11, v10, v10
	v_fmac_f32_e32 v9, v8, v8
	v_add_f32_e32 v8, v11, v9
	v_add_f32_e32 v24, v27, v8
	v_lshlrev_b32_e32 v8, 16, v16
	v_and_b32_e32 v9, 0xffff0000, v16
	v_and_b32_e32 v15, 0xffff0000, v12
	v_lshlrev_b32_e32 v10, 16, v17
	v_and_b32_e32 v11, 0xffff0000, v17
	v_lshlrev_b32_e32 v12, 16, v13
	v_and_b32_e32 v13, 0xffff0000, v13
	v_pk_fma_f32 v[2:3], v[2:3], v[14:15], v[8:9]
	v_pk_fma_f32 v[4:5], v[4:5], v[12:13], v[10:11]
	v_cvt_pk_bf16_f32 v8, v2, v3
	v_mul_f32_e32 v3, v3, v3
	v_fmac_f32_e32 v3, v2, v2
	v_mul_f32_e32 v2, v5, v5
	v_fmac_f32_e32 v2, v4, v4
	v_add_f32_e32 v2, v3, v2
	v_add_f32_e32 v2, v2, v24
	v_mov_b32_e32 v3, v2
	s_nop 1
	v_permlane16_swap_b32_e32 v2, v3
	v_add_f32_e32 v2, v2, v3
	v_mov_b32_e32 v3, v2
	s_nop 1
	v_permlane32_swap_b32_e32 v2, v3
	v_cvt_pk_bf16_f32 v9, v4, v5
	global_store_dwordx4 v[22:23], v[6:9], off offset:256
	s_and_saveexec_b64 s[12:13], s[38:39]
	s_cbranch_execz .LBB0_1005
	v_add_f32_e32 v4, v2, v3
	s_lshl_b32 s2, s57, 2
	v_lshlrev_b64 v[2:3], 6, v[20:21]
	s_ashr_i32 s3, s2, 31
	v_lshl_add_u64 v[2:3], s[8:9], 0, v[2:3]
	v_lshl_add_u64 v[2:3], s[2:3], 2, v[2:3]
	s_lshl_b32 s0, s51, 2
	v_lshl_add_u64 v[2:3], v[2:3], 0, s[0:1]
	global_store_dword v[2:3], v4, off
